# K-loop: s_setprio 0 before last MFMA and loop-counter cmp into MFMA shadow (on top of v9)
# speedup vs baseline: 1.0128x; 1.0128x over previous
; #define PG8_STAGE(bufoff, gbase, voff) do { _Pragma("unroll") for (int _i = 0; _i < 2; ++_i) \
;         __builtin_amdgcn_global_load_lds((const unsigned*)((const char*)(gbase) + (voff)[_i]), (LAS unsigned*)(lds + (bufoff) + ldsw + _i * 8192), 16, 0, 0); } while (0)
; #define PG8_LDA(dst, b, h) do { _Pragma("unroll") for (int m = 0; m < 4; ++m) _Pragma("unroll") for (int k = 0; k < 2; ++k) dst[m][k] = *(const LAS bf16x8*)(lds + PG8_SA(b, h) + aoff + m * 2048 + k * 1024); } while (0)
; #define PG8_LDB(dst, b, h) do { _Pragma("unroll") for (int n = 0; n < 2; ++n) _Pragma("unroll") for (int k = 0; k < 2; ++k) dst[n][k] = *(const LAS bf16x8*)(lds + PG8_SB(b, h) + boff + n * 2048 + k * 1024); } while (0)
; #define PG8_MMA(ai, bj, At, Bt) do { __builtin_amdgcn_s_setprio(1); _Pragma("unroll") for (int m = 0; m < 4; ++m) _Pragma("unroll") for (int n = 0; n < 2; ++n) _Pragma("unroll") for (int k = 0; k < 2; ++k) \
;         acc[ai][bj][m][n] = __builtin_amdgcn_mfma_f32_16x16x32_bf16(Bt[n][k], At[m][k], acc[ai][bj][m][n], 0, 0, 0); __builtin_amdgcn_s_setprio(0); } while (0)
; #define PG8_WAIT_L(n) asm volatile("s_waitcnt lgkmcnt(" #n ")" ::: "memory")
; #define PG8_BAR __builtin_amdgcn_s_barrier()
; #define PG8_SCHED __builtin_amdgcn_sched_barrier(0)
; template <class Epi>
; __device__ __forceinline__ void gemm_phase(LAS unsigned char* lds, const Gemm g, const StaticOrder& S, const Epi& E) {
;     ...
;             const bool last = (t == nt - 2);
;             const char* a1 = cA + (size_t)(t + 1) * kstep;
;             const char* a2 = last ? nA : cA + (size_t)(t + 2) * kstep; const char* b2 = last ? nB : cB + (size_t)(t + 2) * kstep;
;             const char* a3 = a2 + kstep; const char* b3 = b2 + kstep;
;             PG8_LDB(B0, 0, 0); PG8_SCHED; PG8_LDA(At, 0, 0); PG8_STAGE(PG8_SA(1, 1), a1 + hstepA, voffA);
;             PG8_WAIT_L(8); PG8_BAR; PG8_WAIT_L(0); PG8_MMA(0, 0, At, B0); PG8_BAR; PG8_SCHED;
;             PG8_LDB(B1, 0, 1); PG8_STAGE(PG8_SB(0, 0), b2, voffB);
;             PG8_BAR; PG8_WAIT_L(0); PG8_MMA(0, 1, At, B1); PG8_BAR;
;             PG8_LDA(At, 0, 1); PG8_STAGE(PG8_SA(0, 0), a2, voffA);
;             PG8_BAR; PG8_WAIT_L(0); PG8_MMA(1, 0, At, B0); PG8_BAR; PG8_SCHED;
.LBB0_141:
	s_add_u32 s24, s22, 0xfff84000
	s_addc_u32 s25, s23, -1
	s_cmp_eq_u32 s54, 28
	s_cselect_b32 s28, s49, s24
	s_cselect_b32 s29, s15, s25
	s_cselect_b32 s24, s50, s51
	s_cselect_b32 s25, s5, s52
	s_add_u32 s26, s28, 0x4000
	s_addc_u32 s27, s29, 0
	s_add_i32 s55, 0, 0x10000
	v_add_u32_e32 v148, s55, v134
	ds_read_b128 v[136:139], v148
	ds_read_b128 v[140:143], v148 offset:1024
	ds_read_b128 v[144:147], v148 offset:2048
	ds_read_b128 v[148:151], v148 offset:3072
	v_lshl_add_u64 v[188:189], s[22:23], 0, v[128:129]
	s_add_i32 m0, s37, 0xc000
	ds_read_b128 v[156:159], v135
	ds_read_b128 v[160:163], v135 offset:1024
	ds_read_b128 v[164:167], v135 offset:2048
	ds_read_b128 v[168:171], v135 offset:3072
	ds_read_b128 v[172:175], v135 offset:4096
	ds_read_b128 v[176:179], v135 offset:5120
	ds_read_b128 v[180:183], v135 offset:6144
	ds_read_b128 v[184:187], v135 offset:7168
	global_load_lds_dwordx4 v[188:189], off
	s_add_i32 m0, s37, 0xe000
	v_lshl_add_u64 v[188:189], s[22:23], 0, v[130:131]
	global_load_lds_dwordx4 v[188:189], off
	s_waitcnt lgkmcnt(8)
	s_barrier
	s_waitcnt lgkmcnt(0)
	s_setprio 1
	v_mfma_f32_16x16x32_bf16 v[124:127], v[136:139], v[156:159], v[124:127]
	v_mfma_f32_16x16x32_bf16 v[120:123], v[144:147], v[156:159], v[120:123]
	v_mfma_f32_16x16x32_bf16 v[108:111], v[136:139], v[164:167], v[108:111]
	v_mfma_f32_16x16x32_bf16 v[104:107], v[144:147], v[164:167], v[104:107]
	v_mfma_f32_16x16x32_bf16 v[92:95], v[136:139], v[172:175], v[92:95]
	v_mfma_f32_16x16x32_bf16 v[88:91], v[144:147], v[172:175], v[88:91]
	v_mfma_f32_16x16x32_bf16 v[76:79], v[136:139], v[180:183], v[76:79]
	v_mfma_f32_16x16x32_bf16 v[72:75], v[144:147], v[180:183], v[72:75]
	v_mfma_f32_16x16x32_bf16 v[124:127], v[140:143], v[160:163], v[124:127]
	v_mfma_f32_16x16x32_bf16 v[120:123], v[148:151], v[160:163], v[120:123]
	v_mfma_f32_16x16x32_bf16 v[108:111], v[140:143], v[168:171], v[108:111]
	v_mfma_f32_16x16x32_bf16 v[104:107], v[148:151], v[168:171], v[104:107]
	v_mfma_f32_16x16x32_bf16 v[92:95], v[140:143], v[176:179], v[92:95]
	v_mfma_f32_16x16x32_bf16 v[88:91], v[148:151], v[176:179], v[88:91]
	v_mfma_f32_16x16x32_bf16 v[76:79], v[140:143], v[184:187], v[76:79]
	s_setprio 0
	v_mfma_f32_16x16x32_bf16 v[72:75], v[148:151], v[184:187], v[72:75]
	s_barrier
	s_add_i32 s58, 0, 0x14000
	s_add_i32 s55, s55, s36
	v_add_u32_e32 v152, s58, v134
	v_lshl_add_u64 v[204:205], s[24:25], 0, v[128:129]
	s_mov_b32 m0, s55
	ds_read_b128 v[188:191], v152
	ds_read_b128 v[192:195], v152 offset:1024
	ds_read_b128 v[196:199], v152 offset:2048
	ds_read_b128 v[200:203], v152 offset:3072
	global_load_lds_dwordx4 v[204:205], off
	s_add_i32 m0, s55, 0x2000
	v_lshl_add_u64 v[204:205], s[24:25], 0, v[130:131]
	global_load_lds_dwordx4 v[204:205], off
	s_barrier
	s_waitcnt lgkmcnt(0)
	s_setprio 1
	v_mfma_f32_16x16x32_bf16 v[116:119], v[188:191], v[156:159], v[116:119]
	v_mfma_f32_16x16x32_bf16 v[112:115], v[196:199], v[156:159], v[112:115]
	s_mov_b32 m0, s37
	v_lshl_add_u64 v[204:205], s[28:29], 0, v[128:129]
	v_mfma_f32_16x16x32_bf16 v[100:103], v[188:191], v[164:167], v[100:103]
	v_mfma_f32_16x16x32_bf16 v[96:99], v[196:199], v[164:167], v[96:99]
	v_mfma_f32_16x16x32_bf16 v[84:87], v[188:191], v[172:175], v[84:87]
	v_mfma_f32_16x16x32_bf16 v[80:83], v[196:199], v[172:175], v[80:83]
	v_mfma_f32_16x16x32_bf16 v[68:71], v[188:191], v[180:183], v[68:71]
	v_mfma_f32_16x16x32_bf16 v[64:67], v[196:199], v[180:183], v[64:67]
	v_mfma_f32_16x16x32_bf16 v[116:119], v[192:195], v[160:163], v[116:119]
	v_mfma_f32_16x16x32_bf16 v[112:115], v[200:203], v[160:163], v[112:115]
	v_mfma_f32_16x16x32_bf16 v[100:103], v[192:195], v[168:171], v[100:103]
	v_mfma_f32_16x16x32_bf16 v[96:99], v[200:203], v[168:171], v[96:99]
	v_mfma_f32_16x16x32_bf16 v[84:87], v[192:195], v[176:179], v[84:87]
	v_mfma_f32_16x16x32_bf16 v[80:83], v[200:203], v[176:179], v[80:83]
	v_mfma_f32_16x16x32_bf16 v[68:71], v[192:195], v[184:187], v[68:71]
	s_setprio 0
	v_mfma_f32_16x16x32_bf16 v[64:67], v[200:203], v[184:187], v[64:67]
	s_barrier
	ds_read_b128 v[156:159], v135 offset:16384
	ds_read_b128 v[160:163], v135 offset:17408
	ds_read_b128 v[164:167], v135 offset:18432
	ds_read_b128 v[168:171], v135 offset:19456
	ds_read_b128 v[172:175], v135 offset:20480
	ds_read_b128 v[176:179], v135 offset:21504
	ds_read_b128 v[180:183], v135 offset:22528
	ds_read_b128 v[184:187], v135 offset:23552
	global_load_lds_dwordx4 v[204:205], off
	s_mov_b32 m0, s38
	v_lshl_add_u64 v[204:205], s[28:29], 0, v[130:131]
	global_load_lds_dwordx4 v[204:205], off
	s_barrier
	s_waitcnt lgkmcnt(0)
	s_setprio 1
	v_mfma_f32_16x16x32_bf16 v[60:63], v[136:139], v[156:159], v[60:63]
	v_mfma_f32_16x16x32_bf16 v[56:59], v[144:147], v[156:159], v[56:59]
	v_mfma_f32_16x16x32_bf16 v[44:47], v[136:139], v[164:167], v[44:47]
	v_mfma_f32_16x16x32_bf16 v[40:43], v[144:147], v[164:167], v[40:43]
	v_mfma_f32_16x16x32_bf16 v[28:31], v[136:139], v[172:175], v[28:31]
	v_mfma_f32_16x16x32_bf16 v[24:27], v[144:147], v[172:175], v[24:27]
	v_mfma_f32_16x16x32_bf16 v[12:15], v[136:139], v[180:183], v[12:15]
	v_mfma_f32_16x16x32_bf16 v[8:11], v[144:147], v[180:183], v[8:11]
	v_mfma_f32_16x16x32_bf16 v[60:63], v[140:143], v[160:163], v[60:63]
	v_mfma_f32_16x16x32_bf16 v[56:59], v[148:151], v[160:163], v[56:59]
	v_mfma_f32_16x16x32_bf16 v[44:47], v[140:143], v[168:171], v[44:47]
	v_mfma_f32_16x16x32_bf16 v[40:43], v[148:151], v[168:171], v[40:43]
	v_mfma_f32_16x16x32_bf16 v[28:31], v[140:143], v[176:179], v[28:31]
	v_mfma_f32_16x16x32_bf16 v[24:27], v[148:151], v[176:179], v[24:27]
	v_mfma_f32_16x16x32_bf16 v[12:15], v[140:143], v[184:187], v[12:15]
	s_setprio 0
	v_mfma_f32_16x16x32_bf16 v[8:11], v[148:151], v[184:187], v[8:11]
	s_barrier
; #define PG8_STAGE(bufoff, gbase, voff) do { _Pragma("unroll") for (int _i = 0; _i < 2; ++_i) \
;         __builtin_amdgcn_global_load_lds((const unsigned*)((const char*)(gbase) + (voff)[_i]), (LAS unsigned*)(lds + (bufoff) + ldsw + _i * 8192), 16, 0, 0); } while (0)
; #define PG8_LDA(dst, b, h) do { _Pragma("unroll") for (int m = 0; m < 4; ++m) _Pragma("unroll") for (int k = 0; k < 2; ++k) dst[m][k] = *(const LAS bf16x8*)(lds + PG8_SA(b, h) + aoff + m * 2048 + k * 1024); } while (0)
; #define PG8_LDB(dst, b, h) do { _Pragma("unroll") for (int n = 0; n < 2; ++n) _Pragma("unroll") for (int k = 0; k < 2; ++k) dst[n][k] = *(const LAS bf16x8*)(lds + PG8_SB(b, h) + boff + n * 2048 + k * 1024); } while (0)
; #define PG8_MMA(ai, bj, At, Bt) do { __builtin_amdgcn_s_setprio(1); _Pragma("unroll") for (int m = 0; m < 4; ++m) _Pragma("unroll") for (int n = 0; n < 2; ++n) _Pragma("unroll") for (int k = 0; k < 2; ++k) \
;         acc[ai][bj][m][n] = __builtin_amdgcn_mfma_f32_16x16x32_bf16(Bt[n][k], At[m][k], acc[ai][bj][m][n], 0, 0, 0); __builtin_amdgcn_s_setprio(0); } while (0)
; #define PG8_WAIT_V(n) asm volatile("s_waitcnt vmcnt(" #n ")" ::: "memory")
; #define PG8_WAIT_L(n) asm volatile("s_waitcnt lgkmcnt(" #n ")" ::: "memory")
; #define PG8_BAR __builtin_amdgcn_s_barrier()
; #define PG8_SCHED __builtin_amdgcn_sched_barrier(0)
; template <class Epi>
; __device__ __forceinline__ void gemm_phase(LAS unsigned char* lds, const Gemm g, const StaticOrder& S, const Epi& E) {
;     ...
;             PG8_STAGE(PG8_SB(0, 1), b2 + hstepB, voffB);
;             PG8_WAIT_V(6); PG8_BAR; PG8_MMA(1, 1, At, B1); PG8_BAR;
;             PG8_LDB(B0, 1, 0); PG8_SCHED; PG8_LDA(At, 1, 0); PG8_STAGE(PG8_SA(0, 1), a2 + hstepA, voffA);
;             PG8_WAIT_L(8); PG8_BAR; PG8_WAIT_L(0); PG8_MMA(0, 0, At, B0); PG8_BAR; PG8_SCHED;
;             PG8_LDB(B1, 1, 1); PG8_STAGE(PG8_SB(1, 0), b3, voffB);
;             PG8_BAR; PG8_WAIT_L(0); PG8_MMA(0, 1, At, B1); PG8_BAR;
;             PG8_LDA(At, 1, 1); PG8_STAGE(PG8_SA(1, 0), a3, voffA);
;             PG8_BAR; PG8_WAIT_L(0); PG8_MMA(1, 0, At, B0); PG8_BAR; PG8_SCHED;
	s_add_u32 s56, s24, 0x80000
	s_addc_u32 s57, s25, 0
	s_add_i32 s55, s58, s36
	s_mov_b32 m0, s55
	v_lshl_add_u64 v[136:137], s[56:57], 0, v[128:129]
	global_load_lds_dwordx4 v[136:137], off
	s_add_i32 m0, s55, 0x2000
	v_lshl_add_u64 v[136:137], s[56:57], 0, v[130:131]
	global_load_lds_dwordx4 v[136:137], off
	s_waitcnt vmcnt(6)
	s_barrier
	s_setprio 1
	v_mfma_f32_16x16x32_bf16 v[52:55], v[188:191], v[156:159], v[52:55]
	v_mfma_f32_16x16x32_bf16 v[48:51], v[196:199], v[156:159], v[48:51]
	s_add_i32 s55, 0, 0x18000
	v_add_u32_e32 v148, s55, v134
	v_mfma_f32_16x16x32_bf16 v[36:39], v[188:191], v[164:167], v[36:39]
	v_mfma_f32_16x16x32_bf16 v[32:35], v[196:199], v[164:167], v[32:35]
	v_mfma_f32_16x16x32_bf16 v[20:23], v[188:191], v[172:175], v[20:23]
	v_mfma_f32_16x16x32_bf16 v[16:19], v[196:199], v[172:175], v[16:19]
	v_mfma_f32_16x16x32_bf16 v[4:7], v[188:191], v[180:183], v[4:7]
	v_mfma_f32_16x16x32_bf16 v[0:3], v[196:199], v[180:183], v[0:3]
	v_mfma_f32_16x16x32_bf16 v[52:55], v[192:195], v[160:163], v[52:55]
	v_mfma_f32_16x16x32_bf16 v[48:51], v[200:203], v[160:163], v[48:51]
	v_mfma_f32_16x16x32_bf16 v[36:39], v[192:195], v[168:171], v[36:39]
	v_mfma_f32_16x16x32_bf16 v[32:35], v[200:203], v[168:171], v[32:35]
	v_mfma_f32_16x16x32_bf16 v[20:23], v[192:195], v[176:179], v[20:23]
	v_mfma_f32_16x16x32_bf16 v[16:19], v[200:203], v[176:179], v[16:19]
	v_mfma_f32_16x16x32_bf16 v[4:7], v[192:195], v[184:187], v[4:7]
	s_setprio 0
	v_mfma_f32_16x16x32_bf16 v[0:3], v[200:203], v[184:187], v[0:3]
	s_barrier
	ds_read_b128 v[136:139], v148
	ds_read_b128 v[140:143], v148 offset:1024
	ds_read_b128 v[144:147], v148 offset:2048
	ds_read_b128 v[148:151], v148 offset:3072
	s_add_u32 s28, s28, 0x80000
	s_addc_u32 s29, s29, 0
	s_mov_b32 m0, s39
	v_lshl_add_u64 v[188:189], s[28:29], 0, v[128:129]
	ds_read_b128 v[156:159], v135 offset:32768
	ds_read_b128 v[160:163], v135 offset:33792
	ds_read_b128 v[164:167], v135 offset:34816
	ds_read_b128 v[168:171], v135 offset:35840
	ds_read_b128 v[172:175], v135 offset:36864
	ds_read_b128 v[176:179], v135 offset:37888
	ds_read_b128 v[180:183], v135 offset:38912
	ds_read_b128 v[184:187], v135 offset:39936
	global_load_lds_dwordx4 v[188:189], off
	s_mov_b32 m0, s40
	v_lshl_add_u64 v[188:189], s[28:29], 0, v[130:131]
	global_load_lds_dwordx4 v[188:189], off
	s_waitcnt lgkmcnt(8)
	s_barrier
	s_waitcnt lgkmcnt(0)
	s_setprio 1
	v_mfma_f32_16x16x32_bf16 v[124:127], v[136:139], v[156:159], v[124:127]
	v_mfma_f32_16x16x32_bf16 v[120:123], v[144:147], v[156:159], v[120:123]
	v_mfma_f32_16x16x32_bf16 v[108:111], v[136:139], v[164:167], v[108:111]
	v_mfma_f32_16x16x32_bf16 v[104:107], v[144:147], v[164:167], v[104:107]
	v_mfma_f32_16x16x32_bf16 v[92:95], v[136:139], v[172:175], v[92:95]
	v_mfma_f32_16x16x32_bf16 v[88:91], v[144:147], v[172:175], v[88:91]
	v_mfma_f32_16x16x32_bf16 v[76:79], v[136:139], v[180:183], v[76:79]
	v_mfma_f32_16x16x32_bf16 v[72:75], v[144:147], v[180:183], v[72:75]
	v_mfma_f32_16x16x32_bf16 v[124:127], v[140:143], v[160:163], v[124:127]
	v_mfma_f32_16x16x32_bf16 v[120:123], v[148:151], v[160:163], v[120:123]
	v_mfma_f32_16x16x32_bf16 v[108:111], v[140:143], v[168:171], v[108:111]
	v_mfma_f32_16x16x32_bf16 v[104:107], v[148:151], v[168:171], v[104:107]
	v_mfma_f32_16x16x32_bf16 v[92:95], v[140:143], v[176:179], v[92:95]
	v_mfma_f32_16x16x32_bf16 v[88:91], v[148:151], v[176:179], v[88:91]
	v_mfma_f32_16x16x32_bf16 v[76:79], v[140:143], v[184:187], v[76:79]
	s_setprio 0
	v_mfma_f32_16x16x32_bf16 v[72:75], v[148:151], v[184:187], v[72:75]
	s_barrier
	s_add_i32 s56, 0, 0x1c000
	s_add_u32 s28, s24, 0x4000
	s_addc_u32 s29, s25, 0
	s_add_i32 s55, s55, s36
	v_add_u32_e32 v152, s56, v134
	v_lshl_add_u64 v[204:205], s[28:29], 0, v[128:129]
	s_mov_b32 m0, s55
	ds_read_b128 v[188:191], v152
	ds_read_b128 v[192:195], v152 offset:1024
	ds_read_b128 v[196:199], v152 offset:2048
	ds_read_b128 v[200:203], v152 offset:3072
	global_load_lds_dwordx4 v[204:205], off
	s_add_i32 m0, s55, 0x2000
	v_lshl_add_u64 v[204:205], s[28:29], 0, v[130:131]
	global_load_lds_dwordx4 v[204:205], off
	s_barrier
	s_waitcnt lgkmcnt(0)
	s_setprio 1
	v_mfma_f32_16x16x32_bf16 v[116:119], v[188:191], v[156:159], v[116:119]
	v_mfma_f32_16x16x32_bf16 v[112:115], v[196:199], v[156:159], v[112:115]
	s_mov_b32 m0, s43
	v_lshl_add_u64 v[204:205], s[26:27], 0, v[128:129]
	v_mfma_f32_16x16x32_bf16 v[100:103], v[188:191], v[164:167], v[100:103]
	v_mfma_f32_16x16x32_bf16 v[96:99], v[196:199], v[164:167], v[96:99]
	v_mfma_f32_16x16x32_bf16 v[84:87], v[188:191], v[172:175], v[84:87]
	v_mfma_f32_16x16x32_bf16 v[80:83], v[196:199], v[172:175], v[80:83]
	v_mfma_f32_16x16x32_bf16 v[68:71], v[188:191], v[180:183], v[68:71]
	v_mfma_f32_16x16x32_bf16 v[64:67], v[196:199], v[180:183], v[64:67]
	v_mfma_f32_16x16x32_bf16 v[116:119], v[192:195], v[160:163], v[116:119]
	v_mfma_f32_16x16x32_bf16 v[112:115], v[200:203], v[160:163], v[112:115]
	v_mfma_f32_16x16x32_bf16 v[100:103], v[192:195], v[168:171], v[100:103]
	v_mfma_f32_16x16x32_bf16 v[96:99], v[200:203], v[168:171], v[96:99]
	v_mfma_f32_16x16x32_bf16 v[84:87], v[192:195], v[176:179], v[84:87]
	v_mfma_f32_16x16x32_bf16 v[80:83], v[200:203], v[176:179], v[80:83]
	v_mfma_f32_16x16x32_bf16 v[68:71], v[192:195], v[184:187], v[68:71]
	s_setprio 0
	v_mfma_f32_16x16x32_bf16 v[64:67], v[200:203], v[184:187], v[64:67]
	s_barrier
	ds_read_b128 v[156:159], v135 offset:49152
	ds_read_b128 v[160:163], v135 offset:50176
	ds_read_b128 v[164:167], v135 offset:51200
	ds_read_b128 v[168:171], v135 offset:52224
	ds_read_b128 v[172:175], v135 offset:53248
	ds_read_b128 v[176:179], v135 offset:54272
	ds_read_b128 v[180:183], v135 offset:55296
	ds_read_b128 v[184:187], v135 offset:56320
	global_load_lds_dwordx4 v[204:205], off
	s_mov_b32 m0, s44
	v_lshl_add_u64 v[204:205], s[26:27], 0, v[130:131]
	global_load_lds_dwordx4 v[204:205], off
	s_barrier
; __device__ __forceinline__ unsigned cvt_pk_bf16(float lo, float hi) { unsigned r; asm volatile("v_cvt_pk_bf16_f32 %0, %1, %2" : "=v"(r) : "v"(lo), "v"(hi)); return r; }
; #define PG8_STAGE(bufoff, gbase, voff) do { _Pragma("unroll") for (int _i = 0; _i < 2; ++_i) \
;         __builtin_amdgcn_global_load_lds((const unsigned*)((const char*)(gbase) + (voff)[_i]), (LAS unsigned*)(lds + (bufoff) + ldsw + _i * 8192), 16, 0, 0); } while (0)
; #define PG8_MMA(ai, bj, At, Bt) do { __builtin_amdgcn_s_setprio(1); _Pragma("unroll") for (int m = 0; m < 4; ++m) _Pragma("unroll") for (int n = 0; n < 2; ++n) _Pragma("unroll") for (int k = 0; k < 2; ++k) \
;         acc[ai][bj][m][n] = __builtin_amdgcn_mfma_f32_16x16x32_bf16(Bt[n][k], At[m][k], acc[ai][bj][m][n], 0, 0, 0); __builtin_amdgcn_s_setprio(0); } while (0)
; #define PG8_WAIT_V(n) asm volatile("s_waitcnt vmcnt(" #n ")" ::: "memory")
; #define PG8_WAIT_L(n) asm volatile("s_waitcnt lgkmcnt(" #n ")" ::: "memory")
; #define PG8_BAR __builtin_amdgcn_s_barrier()
; #define PG8_SCHED __builtin_amdgcn_sched_barrier(0)
; template <class Epi>
; __device__ __forceinline__ void gemm_phase(LAS unsigned char* lds, const Gemm g, const StaticOrder& S, const Epi& E) {
;     ...
;             PG8_BAR; PG8_WAIT_L(0); PG8_MMA(1, 0, At, B0); PG8_BAR; PG8_SCHED;
;             PG8_STAGE(PG8_SB(1, 1), b3 + hstepB, voffB);
;             PG8_WAIT_V(6); PG8_BAR; PG8_MMA(1, 1, At, B1); PG8_BAR;
;     __device__ __forceinline__ void operator()(const f32x4 (&acc)[2][2][4][2], const Unit& u, int wr, int wc, int fr, int fq) const {
;         const int row0 = u.pm * BM + wr * 64 + fr, col0 = u.pn * BM + wc * 32 + 8 * fq;
; #pragma unroll
;         for (int ai = 0; ai < 2; ++ai)
; #pragma unroll
;             for (int m = 0; m < 4; ++m) {
;                 const int rowi = row0 + ai * HALF + m * 16;
; #pragma unroll
;                 for (int bj = 0; bj < 2; ++bj) {
;                     f32x4 v0 = acc[ai][bj][m][0], v1 = acc[ai][bj][m][1];
; #pragma unroll
;                     for (int j = 0; j < 4; ++j) { const float a = fmaxf(v0[j], 0.f), b = fmaxf(v1[j], 0.f); v0[j] = a * a; v1[j] = b * b; }
;                     u32x4 w; w.x = cvt_pk_bf16(v0[0], v0[1]); w.y = cvt_pk_bf16(v0[2], v0[3]); w.z = cvt_pk_bf16(v1[0], v1[1]); w.w = cvt_pk_bf16(v1[2], v1[3]);
;                     *(u32x4*)(O + tiled_off(rowi, col0 + bj * HALF, DFF / 64)) = w;
	s_waitcnt lgkmcnt(0)
	s_setprio 1
	v_mfma_f32_16x16x32_bf16 v[60:63], v[136:139], v[156:159], v[60:63]
	v_mfma_f32_16x16x32_bf16 v[56:59], v[144:147], v[156:159], v[56:59]
	v_mfma_f32_16x16x32_bf16 v[44:47], v[136:139], v[164:167], v[44:47]
	v_mfma_f32_16x16x32_bf16 v[40:43], v[144:147], v[164:167], v[40:43]
	v_mfma_f32_16x16x32_bf16 v[28:31], v[136:139], v[172:175], v[28:31]
	v_mfma_f32_16x16x32_bf16 v[24:27], v[144:147], v[172:175], v[24:27]
	v_mfma_f32_16x16x32_bf16 v[12:15], v[136:139], v[180:183], v[12:15]
	v_mfma_f32_16x16x32_bf16 v[8:11], v[144:147], v[180:183], v[8:11]
	v_mfma_f32_16x16x32_bf16 v[60:63], v[140:143], v[160:163], v[60:63]
	v_mfma_f32_16x16x32_bf16 v[56:59], v[148:151], v[160:163], v[56:59]
	v_mfma_f32_16x16x32_bf16 v[44:47], v[140:143], v[168:171], v[44:47]
	v_mfma_f32_16x16x32_bf16 v[40:43], v[148:151], v[168:171], v[40:43]
	v_mfma_f32_16x16x32_bf16 v[28:31], v[140:143], v[176:179], v[28:31]
	v_mfma_f32_16x16x32_bf16 v[24:27], v[148:151], v[176:179], v[24:27]
	v_mfma_f32_16x16x32_bf16 v[12:15], v[140:143], v[184:187], v[12:15]
	s_setprio 0
	v_mfma_f32_16x16x32_bf16 v[8:11], v[148:151], v[184:187], v[8:11]
	s_barrier
	s_add_u32 s24, s24, 0x84000
	s_addc_u32 s25, s25, 0
	s_add_i32 s26, s56, s36
	s_mov_b32 m0, s26
	v_lshl_add_u64 v[136:137], s[24:25], 0, v[128:129]
	global_load_lds_dwordx4 v[136:137], off
	s_add_i32 m0, s26, 0x2000
	v_lshl_add_u64 v[136:137], s[24:25], 0, v[130:131]
	global_load_lds_dwordx4 v[136:137], off
	s_waitcnt vmcnt(6)
	s_barrier
	s_setprio 1
	v_mfma_f32_16x16x32_bf16 v[52:55], v[188:191], v[156:159], v[52:55]
	v_mfma_f32_16x16x32_bf16 v[48:51], v[196:199], v[156:159], v[48:51]
	s_add_i32 s54, s54, 2
	s_add_u32 s22, s22, 0x8000
	s_addc_u32 s23, s23, 0
	s_add_u32 s51, s51, 0x8000
	s_addc_u32 s52, s52, 0
	v_mfma_f32_16x16x32_bf16 v[36:39], v[188:191], v[164:167], v[36:39]
	v_mfma_f32_16x16x32_bf16 v[32:35], v[196:199], v[164:167], v[32:35]
	v_mfma_f32_16x16x32_bf16 v[20:23], v[188:191], v[172:175], v[20:23]
	v_mfma_f32_16x16x32_bf16 v[16:19], v[196:199], v[172:175], v[16:19]
	v_mfma_f32_16x16x32_bf16 v[4:7], v[188:191], v[180:183], v[4:7]
	v_mfma_f32_16x16x32_bf16 v[0:3], v[196:199], v[180:183], v[0:3]
	v_mfma_f32_16x16x32_bf16 v[52:55], v[192:195], v[160:163], v[52:55]
	v_mfma_f32_16x16x32_bf16 v[48:51], v[200:203], v[160:163], v[48:51]
	v_mfma_f32_16x16x32_bf16 v[36:39], v[192:195], v[168:171], v[36:39]
	v_mfma_f32_16x16x32_bf16 v[32:35], v[200:203], v[168:171], v[32:35]
	v_mfma_f32_16x16x32_bf16 v[20:23], v[192:195], v[176:179], v[20:23]
	v_mfma_f32_16x16x32_bf16 v[16:19], v[200:203], v[176:179], v[16:19]
	v_mfma_f32_16x16x32_bf16 v[4:7], v[192:195], v[184:187], v[4:7]
	s_cmp_gt_u32 s54, 29
	s_setprio 0
	v_mfma_f32_16x16x32_bf16 v[0:3], v[200:203], v[184:187], v[0:3]
	s_barrier
	s_cbranch_scc0 .LBB0_141
	s_lshl_b32 s24, s20, 8
	s_lshl_b32 s5, s21, 8
	s_add_i32 s24, s24, s41
	s_or_b32 s5, s5, s42
	s_and_b32 s22, s24, 0xffffff80
	s_ashr_i32 s5, s5, 6
	s_add_i32 s20, s22, s5
	s_ashr_i32 s21, s20, 31
	v_max_f32_e32 v120, 0, v120
	s_lshl_b64 s[20:21], s[20:21], 14
	v_readlane_b32 s26, v252, 57
	v_or_b32_e32 v136, s24, v132
	v_mul_f32_e32 v140, v120, v120
	v_max_f32_e32 v121, 0, v121
	v_max_f32_e32 v122, 0, v122
	v_readlane_b32 s27, v252, 58
	s_add_u32 s20, s26, s20
	v_lshlrev_b32_e32 v137, 6, v136
	s_movk_i32 s28, 0x3c0
	v_lshlrev_b32_e32 v138, 2, v136
	v_max_f32_e32 v120, 0, v125
	v_mul_f32_e32 v125, v121, v121
	v_max_f32_e32 v121, v126, v126
	v_mul_f32_e32 v126, v122, v122
	s_addc_u32 s21, s27, s21
	s_or_b32 s15, s5, 2
	v_and_or_b32 v137, v137, s28, v133
	v_and_b32_e32 v138, 32, v138
	v_max_f32_e32 v124, 0, v124
	v_mul_f32_e32 v120, v120, v120
	v_max_f32_e32 v121, 0, v121
	v_max_f32_e32 v122, 0, v127
	v_max_f32_e32 v123, 0, v123
	s_add_i32 s22, s15, s22
	v_bitop3_b32 v139, v137, s46, v138 bitop3:0xde
	v_mul_f32_e32 v124, v124, v124
	v_mul_f32_e32 v121, v121, v121
	v_mul_f32_e32 v122, v122, v122
	v_mul_f32_e32 v123, v123, v123
	v_cvt_pk_bf16_f32 v120, v124, v120
	v_max_f32_e32 v112, 0, v112
	v_max_f32_e32 v113, 0, v113
	s_ashr_i32 s23, s22, 31
	v_cvt_pk_bf16_f32 v121, v121, v122
	v_cvt_pk_bf16_f32 v122, v140, v125
	v_cvt_pk_bf16_f32 v123, v126, v123
	global_store_dwordx4 v139, v[120:123], s[20:21]
	v_max_f32_e32 v114, 0, v114
	s_lshl_b64 s[22:23], s[22:23], 14
	v_mul_f32_e32 v120, v112, v112
	v_max_f32_e32 v112, v117, v117
	v_mul_f32_e32 v117, v113, v113
	v_max_f32_e32 v112, 0, v112
	v_max_f32_e32 v113, 0, v118
	v_mul_f32_e32 v118, v114, v114
	s_add_u32 s22, s26, s22
	v_max_f32_e32 v116, 0, v116
	v_mul_f32_e32 v112, v112, v112
	v_mul_f32_e32 v113, v113, v113
	v_max_f32_e32 v114, 0, v119
	v_max_f32_e32 v115, 0, v115
	s_addc_u32 s23, s27, s23
	s_or_b32 s25, s24, 16
	v_mul_f32_e32 v116, v116, v116
	v_mul_f32_e32 v114, v114, v114
	v_mul_f32_e32 v115, v115, v115
	v_cvt_pk_bf16_f32 v112, v116, v112
	v_cvt_pk_bf16_f32 v113, v113, v114
	s_lshr_b32 s25, s25, 3
	v_max_f32_e32 v104, 0, v104
	v_cvt_pk_bf16_f32 v114, v120, v117
	v_cvt_pk_bf16_f32 v115, v118, v115
	global_store_dwordx4 v139, v[112:115], s[22:23]
	s_and_b32 s25, s25, 10
	v_max_f32_e32 v105, 0, v105
	v_mul_f32_e32 v113, v104, v104
	v_max_f32_e32 v106, 0, v106
	s_or_b32 s25, s25, s45
	v_max_f32_e32 v104, 0, v109
	v_mul_f32_e32 v109, v105, v105
	v_max_f32_e32 v105, v110, v110
	v_mul_f32_e32 v110, v106, v106
	s_lshl_b32 s25, s25, 10
	v_max_f32_e32 v108, 0, v108
	v_mul_f32_e32 v104, v104, v104
	v_max_f32_e32 v105, 0, v105
	v_max_f32_e32 v106, 0, v111
	v_max_f32_e32 v107, 0, v107
	v_bitop3_b32 v112, v137, s25, v138 bitop3:0xde
	v_mul_f32_e32 v108, v108, v108
	v_mul_f32_e32 v105, v105, v105
	v_mul_f32_e32 v106, v106, v106
	v_mul_f32_e32 v107, v107, v107
; __device__ __forceinline__ unsigned cvt_pk_bf16(float lo, float hi) { unsigned r; asm volatile("v_cvt_pk_bf16_f32 %0, %1, %2" : "=v"(r) : "v"(lo), "v"(hi)); return r; }
;     __device__ __forceinline__ void operator()(const f32x4 (&acc)[2][2][4][2], const Unit& u, int wr, int wc, int fr, int fq) const {
;     ...
;         for (int ai = 0; ai < 2; ++ai)
; #pragma unroll
;             for (int m = 0; m < 4; ++m) {
;                 const int rowi = row0 + ai * HALF + m * 16;
; #pragma unroll
;                 for (int bj = 0; bj < 2; ++bj) {
;                     f32x4 v0 = acc[ai][bj][m][0], v1 = acc[ai][bj][m][1];
; #pragma unroll
;                     for (int j = 0; j < 4; ++j) { const float a = fmaxf(v0[j], 0.f), b = fmaxf(v1[j], 0.f); v0[j] = a * a; v1[j] = b * b; }
;                     u32x4 w; w.x = cvt_pk_bf16(v0[0], v0[1]); w.y = cvt_pk_bf16(v0[2], v0[3]); w.z = cvt_pk_bf16(v1[0], v1[1]); w.w = cvt_pk_bf16(v1[2], v1[3]);
;                     *(u32x4*)(O + tiled_off(rowi, col0 + bj * HALF, DFF / 64)) = w;
	v_cvt_pk_bf16_f32 v104, v108, v104
	v_max_f32_e32 v96, 0, v96
	v_max_f32_e32 v97, 0, v97
	v_cvt_pk_bf16_f32 v105, v105, v106
	v_cvt_pk_bf16_f32 v106, v113, v109
	v_cvt_pk_bf16_f32 v107, v110, v107
	global_store_dwordx4 v112, v[104:107], s[20:21]
	s_nop 0
	v_max_f32_e32 v98, 0, v98
	v_mul_f32_e32 v104, v96, v96
	v_max_f32_e32 v96, v101, v101
	v_mul_f32_e32 v101, v97, v97
	v_max_f32_e32 v96, 0, v96
	v_max_f32_e32 v97, 0, v102
	v_mul_f32_e32 v102, v98, v98
	v_max_f32_e32 v100, 0, v100
	v_mul_f32_e32 v96, v96, v96
	v_mul_f32_e32 v97, v97, v97
	v_max_f32_e32 v98, 0, v103
	v_max_f32_e32 v99, 0, v99
	s_or_b32 s25, s24, 32
	v_mul_f32_e32 v100, v100, v100
	v_mul_f32_e32 v98, v98, v98
	v_mul_f32_e32 v99, v99, v99
	v_cvt_pk_bf16_f32 v96, v100, v96
	v_cvt_pk_bf16_f32 v97, v97, v98
	s_lshr_b32 s25, s25, 3
	v_max_f32_e32 v88, 0, v88
	v_cvt_pk_bf16_f32 v98, v104, v101
	v_cvt_pk_bf16_f32 v99, v102, v99
	global_store_dwordx4 v112, v[96:99], s[22:23]
	s_and_b32 s25, s25, 12
	v_max_f32_e32 v89, 0, v89
	v_mul_f32_e32 v97, v88, v88
	v_max_f32_e32 v90, 0, v90
	s_or_b32 s25, s25, s45
	v_max_f32_e32 v88, 0, v93
	v_mul_f32_e32 v93, v89, v89
	v_max_f32_e32 v89, v94, v94
	v_mul_f32_e32 v94, v90, v90
	s_lshl_b32 s25, s25, 10
	v_max_f32_e32 v92, 0, v92
	v_mul_f32_e32 v88, v88, v88
	v_max_f32_e32 v89, 0, v89
	v_max_f32_e32 v90, 0, v95
	v_max_f32_e32 v91, 0, v91
	v_bitop3_b32 v96, v137, s25, v138 bitop3:0xde
	v_mul_f32_e32 v92, v92, v92
	v_mul_f32_e32 v89, v89, v89
	v_mul_f32_e32 v90, v90, v90
	v_mul_f32_e32 v91, v91, v91
	v_cvt_pk_bf16_f32 v88, v92, v88
	v_max_f32_e32 v80, 0, v80
	v_max_f32_e32 v81, 0, v81
	v_cvt_pk_bf16_f32 v89, v89, v90
	v_cvt_pk_bf16_f32 v90, v97, v93
	v_cvt_pk_bf16_f32 v91, v94, v91
	global_store_dwordx4 v96, v[88:91], s[20:21]
	s_nop 0
	v_max_f32_e32 v82, 0, v82
	v_mul_f32_e32 v88, v80, v80
	v_max_f32_e32 v80, v85, v85
	v_mul_f32_e32 v85, v81, v81
	v_max_f32_e32 v80, 0, v80
	v_max_f32_e32 v81, 0, v86
	v_mul_f32_e32 v86, v82, v82
	v_max_f32_e32 v84, 0, v84
	v_mul_f32_e32 v80, v80, v80
	v_mul_f32_e32 v81, v81, v81
	v_max_f32_e32 v82, 0, v87
	v_max_f32_e32 v83, 0, v83
	s_or_b32 s24, s24, 48
	v_mul_f32_e32 v84, v84, v84
	v_mul_f32_e32 v82, v82, v82
	v_mul_f32_e32 v83, v83, v83
	v_cvt_pk_bf16_f32 v80, v84, v80
	v_cvt_pk_bf16_f32 v81, v81, v82
	s_lshr_b32 s24, s24, 3
	v_max_f32_e32 v72, 0, v72
	v_cvt_pk_bf16_f32 v82, v88, v85
	v_cvt_pk_bf16_f32 v83, v86, v83
	global_store_dwordx4 v96, v[80:83], s[22:23]
	s_and_b32 s24, s24, 14
	v_max_f32_e32 v73, 0, v73
	v_mul_f32_e32 v81, v72, v72
	v_max_f32_e32 v74, 0, v74
	s_or_b32 s24, s24, s45
	v_max_f32_e32 v72, 0, v77
	v_mul_f32_e32 v77, v73, v73
	v_max_f32_e32 v73, v78, v78
	v_mul_f32_e32 v78, v74, v74
	s_lshl_b32 s24, s24, 10
	v_max_f32_e32 v76, 0, v76
	v_mul_f32_e32 v72, v72, v72
	v_max_f32_e32 v73, 0, v73
	v_max_f32_e32 v74, 0, v79
	v_max_f32_e32 v75, 0, v75
	v_bitop3_b32 v80, v137, s24, v138 bitop3:0xde
	v_mul_f32_e32 v76, v76, v76
	v_mul_f32_e32 v73, v73, v73
	v_mul_f32_e32 v74, v74, v74
	v_mul_f32_e32 v75, v75, v75
	v_cvt_pk_bf16_f32 v72, v76, v72
	v_max_f32_e32 v64, 0, v64
	v_cvt_pk_bf16_f32 v73, v73, v74
	v_cvt_pk_bf16_f32 v74, v81, v77
	v_cvt_pk_bf16_f32 v75, v78, v75
	global_store_dwordx4 v80, v[72:75], s[20:21]
	v_max_f32_e32 v65, 0, v65
	v_max_f32_e32 v66, 0, v66
	v_mul_f32_e32 v72, v64, v64
	v_max_f32_e32 v64, 0, v69
	v_mul_f32_e32 v69, v65, v65
	v_max_f32_e32 v65, v70, v70
	v_mul_f32_e32 v70, v66, v66
	v_max_f32_e32 v68, 0, v68
	v_mul_f32_e32 v64, v64, v64
	v_max_f32_e32 v65, 0, v65
	v_max_f32_e32 v66, 0, v71
	v_max_f32_e32 v67, 0, v67
	v_mul_f32_e32 v68, v68, v68
	v_mul_f32_e32 v65, v65, v65
	v_mul_f32_e32 v66, v66, v66
	v_mul_f32_e32 v67, v67, v67
	v_cvt_pk_bf16_f32 v64, v68, v64
	v_cvt_pk_bf16_f32 v65, v65, v66
	v_cvt_pk_bf16_f32 v66, v72, v69
	v_cvt_pk_bf16_f32 v67, v70, v67
	global_store_dwordx4 v80, v[64:67], s[22:23]
	s_nop 0
	v_max_f32_e32 v56, 0, v56
	v_add_u32_e32 v64, 0x80, v136
	v_and_b32_e32 v65, 0xffffff80, v64
	v_lshlrev_b32_e32 v66, 6, v64
	v_lshlrev_b32_e32 v64, 2, v64
	v_and_or_b32 v66, v66, s28, v133
	v_and_b32_e32 v64, 32, v64
	v_bitop3_b32 v152, v66, s46, v64 bitop3:0xde
	v_mul_f32_e32 v64, v56, v56
	v_max_f32_e32 v57, 0, v57
	v_max_f32_e32 v58, 0, v58
	v_max_f32_e32 v60, 0, v60
	v_max_f32_e32 v56, 0, v61
	v_mul_f32_e32 v61, v57, v57
	v_max_f32_e32 v57, v62, v62
	v_mul_f32_e32 v62, v58, v58
	v_mul_f32_e32 v60, v60, v60
	v_mul_f32_e32 v56, v56, v56
	v_max_f32_e32 v57, 0, v57
	v_max_f32_e32 v58, 0, v63
	v_mul_f32_e32 v57, v57, v57
	v_mul_f32_e32 v58, v58, v58
	v_cvt_pk_bf16_f32 v56, v60, v56
	v_add_u32_e32 v60, s5, v65
	v_cvt_pk_bf16_f32 v57, v57, v58
	v_cvt_pk_bf16_f32 v58, v64, v61
	v_ashrrev_i32_e32 v61, 31, v60
	v_max_f32_e32 v59, 0, v59
	v_lshlrev_b64 v[60:61], 14, v[60:61]
	v_mul_f32_e32 v59, v59, v59
	v_lshl_add_u64 v[60:61], s[26:27], 0, v[60:61]
	v_cvt_pk_bf16_f32 v59, v62, v59
	v_lshl_add_u64 v[62:63], v[60:61], 0, v[152:153]
	v_max_f32_e32 v48, 0, v48
	global_store_dwordx4 v[62:63], v[56:59], off
	s_nop 0
	v_max_f32_e32 v49, 0, v49
	v_mul_f32_e32 v56, v48, v48
	v_max_f32_e32 v50, 0, v50
	v_max_f32_e32 v52, 0, v52
	v_max_f32_e32 v48, 0, v53
	v_mul_f32_e32 v53, v49, v49
	v_max_f32_e32 v49, v54, v54
	v_mul_f32_e32 v54, v50, v50
	v_mul_f32_e32 v52, v52, v52
	v_mul_f32_e32 v48, v48, v48
	v_max_f32_e32 v49, 0, v49
	v_max_f32_e32 v50, 0, v55
	v_mul_f32_e32 v49, v49, v49
	v_mul_f32_e32 v50, v50, v50
	v_cvt_pk_bf16_f32 v48, v52, v48
	v_add_u32_e32 v52, s15, v65
	v_cvt_pk_bf16_f32 v49, v49, v50
	v_cvt_pk_bf16_f32 v50, v56, v53
	v_ashrrev_i32_e32 v53, 31, v52
	v_max_f32_e32 v51, 0, v51
	v_lshlrev_b64 v[52:53], 14, v[52:53]
	v_mul_f32_e32 v51, v51, v51
; __device__ __forceinline__ unsigned cvt_pk_bf16(float lo, float hi) { unsigned r; asm volatile("v_cvt_pk_bf16_f32 %0, %1, %2" : "=v"(r) : "v"(lo), "v"(hi)); return r; }
; #define PG8_WAIT_V(n) asm volatile("s_waitcnt vmcnt(" #n ")" ::: "memory")
; #define PG8_BAR __builtin_amdgcn_s_barrier()
; template <class Epi>
; __device__ __forceinline__ void gemm_phase(LAS unsigned char* lds, const Gemm g, const StaticOrder& S, const Epi& E) {
;     ...
;         if (!has_next) break;
; #pragma unroll
;         for (int a = 0; a < 2; ++a)
; #pragma unroll
;             for (int b = 0; b < 2; ++b)
; #pragma unroll
;                 for (int m = 0; m < 4; ++m)
; #pragma unroll
;                     for (int n = 0; n < 2; ++n) acc[a][b][m][n] = (f32x4){0.f, 0.f, 0.f, 0.f};
;         cur = nxt; cA = nA; cB = nB; ++ui;
;     }
;     PG8_WAIT_V(0);
;     if (wr == 0) PG8_BAR;
;     __device__ __forceinline__ void operator()(const f32x4 (&acc)[2][2][4][2], const Unit& u, int wr, int wc, int fr, int fq) const {
;     ...
;         for (int ai = 0; ai < 2; ++ai)
; #pragma unroll
;             for (int m = 0; m < 4; ++m) {
;                 const int rowi = row0 + ai * HALF + m * 16;
; #pragma unroll
;                 for (int bj = 0; bj < 2; ++bj) {
;                     f32x4 v0 = acc[ai][bj][m][0], v1 = acc[ai][bj][m][1];
; #pragma unroll
;                     for (int j = 0; j < 4; ++j) { const float a = fmaxf(v0[j], 0.f), b = fmaxf(v1[j], 0.f); v0[j] = a * a; v1[j] = b * b; }
;                     u32x4 w; w.x = cvt_pk_bf16(v0[0], v0[1]); w.y = cvt_pk_bf16(v0[2], v0[3]); w.z = cvt_pk_bf16(v1[0], v1[1]); w.w = cvt_pk_bf16(v1[2], v1[3]);
;                     *(u32x4*)(O + tiled_off(rowi, col0 + bj * HALF, DFF / 64)) = w;
	v_lshl_add_u64 v[52:53], s[26:27], 0, v[52:53]
	v_cvt_pk_bf16_f32 v51, v54, v51
	v_lshl_add_u64 v[54:55], v[52:53], 0, v[152:153]
	global_store_dwordx4 v[54:55], v[48:51], off
	s_nop 1
	v_add_u32_e32 v48, 0x90, v136
	v_lshrrev_b32_e32 v49, 3, v48
	v_and_or_b32 v49, v49, 10, s45
	v_lshlrev_b32_e32 v50, 6, v48
	v_lshlrev_b32_e32 v48, 2, v48
	v_and_or_b32 v50, v50, s28, v133
	v_lshlrev_b32_e32 v49, 10, v49
	v_and_b32_e32 v48, 32, v48
	v_max_f32_e32 v40, 0, v40
	v_max_f32_e32 v41, 0, v41
	v_max_f32_e32 v42, 0, v42
	v_bitop3_b32 v152, v50, v49, v48 bitop3:0xde
	v_mul_f32_e32 v48, v40, v40
	v_max_f32_e32 v40, v45, v45
	v_mul_f32_e32 v45, v41, v41
	v_max_f32_e32 v41, v46, v46
	v_mul_f32_e32 v46, v42, v42
	v_max_f32_e32 v44, 0, v44
	v_max_f32_e32 v40, 0, v40
	v_max_f32_e32 v41, 0, v41
	v_max_f32_e32 v42, 0, v47
	v_mul_f32_e32 v44, v44, v44
	v_mul_f32_e32 v40, v40, v40
	v_mul_f32_e32 v41, v41, v41
	v_max_f32_e32 v43, 0, v43
	v_mul_f32_e32 v42, v42, v42
	v_mul_f32_e32 v43, v43, v43
	v_cvt_pk_bf16_f32 v40, v44, v40
	v_cvt_pk_bf16_f32 v41, v41, v42
	v_cvt_pk_bf16_f32 v42, v48, v45
	v_lshl_add_u64 v[44:45], v[60:61], 0, v[152:153]
	v_max_f32_e32 v32, 0, v32
	v_max_f32_e32 v33, 0, v33
	v_max_f32_e32 v34, 0, v34
	v_cvt_pk_bf16_f32 v43, v46, v43
	global_store_dwordx4 v[44:45], v[40:43], off
	s_nop 0
	v_max_f32_e32 v36, 0, v36
	v_mul_f32_e32 v40, v32, v32
	v_max_f32_e32 v32, v37, v37
	v_mul_f32_e32 v37, v33, v33
	v_max_f32_e32 v33, v38, v38
	v_mul_f32_e32 v38, v34, v34
	v_max_f32_e32 v32, 0, v32
	v_max_f32_e32 v33, 0, v33
	v_max_f32_e32 v34, 0, v39
	v_mul_f32_e32 v36, v36, v36
	v_mul_f32_e32 v32, v32, v32
	v_mul_f32_e32 v33, v33, v33
	v_max_f32_e32 v35, 0, v35
	v_mul_f32_e32 v34, v34, v34
	v_mul_f32_e32 v35, v35, v35
	v_cvt_pk_bf16_f32 v32, v36, v32
	v_cvt_pk_bf16_f32 v33, v33, v34
	v_cvt_pk_bf16_f32 v34, v40, v37
	v_lshl_add_u64 v[36:37], v[52:53], 0, v[152:153]
	v_cvt_pk_bf16_f32 v35, v38, v35
	global_store_dwordx4 v[36:37], v[32:35], off
	s_nop 1
	v_add_u32_e32 v32, 0xa0, v136
	v_lshrrev_b32_e32 v33, 3, v32
	v_and_or_b32 v33, v33, 12, s45
	v_lshlrev_b32_e32 v34, 6, v32
	v_lshlrev_b32_e32 v32, 2, v32
	v_and_or_b32 v34, v34, s28, v133
	v_lshlrev_b32_e32 v33, 10, v33
	v_and_b32_e32 v32, 32, v32
	v_max_f32_e32 v24, 0, v24
	v_max_f32_e32 v25, 0, v25
	v_max_f32_e32 v26, 0, v26
	v_bitop3_b32 v152, v34, v33, v32 bitop3:0xde
	v_mul_f32_e32 v32, v24, v24
	v_max_f32_e32 v24, v29, v29
	v_mul_f32_e32 v29, v25, v25
	v_max_f32_e32 v25, v30, v30
	v_mul_f32_e32 v30, v26, v26
	v_max_f32_e32 v28, 0, v28
	v_max_f32_e32 v24, 0, v24
	v_max_f32_e32 v25, 0, v25
	v_max_f32_e32 v26, 0, v31
	v_mul_f32_e32 v28, v28, v28
	v_mul_f32_e32 v24, v24, v24
	v_mul_f32_e32 v25, v25, v25
	v_max_f32_e32 v27, 0, v27
	v_mul_f32_e32 v26, v26, v26
	v_mul_f32_e32 v27, v27, v27
	v_cvt_pk_bf16_f32 v24, v28, v24
	v_cvt_pk_bf16_f32 v25, v25, v26
	v_cvt_pk_bf16_f32 v26, v32, v29
	v_lshl_add_u64 v[28:29], v[60:61], 0, v[152:153]
	v_max_f32_e32 v16, 0, v16
	v_max_f32_e32 v17, 0, v17
	v_max_f32_e32 v18, 0, v18
	v_cvt_pk_bf16_f32 v27, v30, v27
	global_store_dwordx4 v[28:29], v[24:27], off
	s_nop 0
	v_max_f32_e32 v20, 0, v20
	v_mul_f32_e32 v24, v16, v16
	v_max_f32_e32 v16, v21, v21
	v_mul_f32_e32 v21, v17, v17
	v_max_f32_e32 v17, v22, v22
	v_mul_f32_e32 v22, v18, v18
	v_max_f32_e32 v16, 0, v16
	v_max_f32_e32 v17, 0, v17
	v_max_f32_e32 v18, 0, v23
	v_mul_f32_e32 v20, v20, v20
	v_mul_f32_e32 v16, v16, v16
	v_mul_f32_e32 v17, v17, v17
	v_max_f32_e32 v19, 0, v19
	v_mul_f32_e32 v18, v18, v18
	v_mul_f32_e32 v19, v19, v19
	v_cvt_pk_bf16_f32 v16, v20, v16
	v_cvt_pk_bf16_f32 v17, v17, v18
	v_cvt_pk_bf16_f32 v18, v24, v21
	v_lshl_add_u64 v[20:21], v[52:53], 0, v[152:153]
	v_cvt_pk_bf16_f32 v19, v22, v19
	global_store_dwordx4 v[20:21], v[16:19], off
	s_nop 1
	v_add_u32_e32 v16, 0xb0, v136
	v_lshrrev_b32_e32 v17, 3, v16
	v_and_or_b32 v17, v17, 14, s45
	v_lshlrev_b32_e32 v18, 6, v16
	v_lshlrev_b32_e32 v16, 2, v16
	v_and_or_b32 v18, v18, s28, v133
	v_lshlrev_b32_e32 v17, 10, v17
	v_and_b32_e32 v16, 32, v16
	v_max_f32_e32 v8, 0, v8
	v_max_f32_e32 v9, 0, v9
	v_max_f32_e32 v10, 0, v10
	v_bitop3_b32 v152, v18, v17, v16 bitop3:0xde
	v_mul_f32_e32 v16, v8, v8
	v_max_f32_e32 v8, v13, v13
	v_mul_f32_e32 v13, v9, v9
	v_max_f32_e32 v9, v14, v14
	v_mul_f32_e32 v14, v10, v10
	v_max_f32_e32 v12, 0, v12
	v_max_f32_e32 v8, 0, v8
	v_max_f32_e32 v9, 0, v9
	v_max_f32_e32 v10, 0, v15
	v_mul_f32_e32 v12, v12, v12
	v_mul_f32_e32 v8, v8, v8
	v_mul_f32_e32 v9, v9, v9
	v_max_f32_e32 v11, 0, v11
	v_mul_f32_e32 v10, v10, v10
	v_mul_f32_e32 v11, v11, v11
	v_cvt_pk_bf16_f32 v8, v12, v8
	v_cvt_pk_bf16_f32 v9, v9, v10
	v_cvt_pk_bf16_f32 v10, v16, v13
	v_lshl_add_u64 v[12:13], v[60:61], 0, v[152:153]
	v_max_f32_e32 v0, 0, v0
	v_max_f32_e32 v1, 0, v1
	v_max_f32_e32 v2, 0, v2
	v_cvt_pk_bf16_f32 v11, v14, v11
	global_store_dwordx4 v[12:13], v[8:11], off
	s_nop 0
	v_max_f32_e32 v4, 0, v4
	v_mul_f32_e32 v8, v0, v0
	v_max_f32_e32 v0, v5, v5
	v_mul_f32_e32 v5, v1, v1
	v_max_f32_e32 v1, v6, v6
	v_mul_f32_e32 v6, v2, v2
	v_max_f32_e32 v0, 0, v0
	v_max_f32_e32 v1, 0, v1
	v_max_f32_e32 v2, 0, v7
	v_mul_f32_e32 v4, v4, v4
	v_mul_f32_e32 v0, v0, v0
	v_mul_f32_e32 v1, v1, v1
	v_max_f32_e32 v3, 0, v3
	v_mul_f32_e32 v2, v2, v2
	s_mov_b32 s54, 0xd00ab22c
	v_mul_f32_e32 v3, v3, v3
	v_cvt_pk_bf16_f32 v0, v4, v0
	v_cvt_pk_bf16_f32 v1, v1, v2
	v_cvt_pk_bf16_f32 v2, v8, v5
	v_lshl_add_u64 v[4:5], v[52:53], 0, v[152:153]
	s_and_b64 vcc, exec, s[0:1]
	s_mov_b32 s21, s4
	s_mov_b32 s20, s14
	s_mov_b64 s[24:25], s[18:19]
	s_mov_b64 s[22:23], s[16:17]
	s_mov_b32 s55, 0x3febb5fa
	v_cvt_pk_bf16_f32 v3, v6, v3
	global_store_dwordx4 v[4:5], v[0:3], off
	s_cbranch_vccz .LBB0_134
	s_waitcnt vmcnt(0)
	s_cmpk_gt_u32 s31, 0xff
	s_cbranch_scc1 .LBB0_145
	s_barrier

; #define PG8_STAGE(bufoff, gbase, voff) do { _Pragma("unroll") for (int _i = 0; _i < 2; ++_i) \
;         __builtin_amdgcn_global_load_lds((const unsigned*)((const char*)(gbase) + (voff)[_i]), (LAS unsigned*)(lds + (bufoff) + ldsw + _i * 8192), 16, 0, 0); } while (0)
; #define PG8_LDA(dst, b, h) do { _Pragma("unroll") for (int m = 0; m < 4; ++m) _Pragma("unroll") for (int k = 0; k < 2; ++k) dst[m][k] = *(const LAS bf16x8*)(lds + PG8_SA(b, h) + aoff + m * 2048 + k * 1024); } while (0)
; #define PG8_LDB(dst, b, h) do { _Pragma("unroll") for (int n = 0; n < 2; ++n) _Pragma("unroll") for (int k = 0; k < 2; ++k) dst[n][k] = *(const LAS bf16x8*)(lds + PG8_SB(b, h) + boff + n * 2048 + k * 1024); } while (0)
; #define PG8_MMA(ai, bj, At, Bt) do { __builtin_amdgcn_s_setprio(1); _Pragma("unroll") for (int m = 0; m < 4; ++m) _Pragma("unroll") for (int n = 0; n < 2; ++n) _Pragma("unroll") for (int k = 0; k < 2; ++k) \
;         acc[ai][bj][m][n] = __builtin_amdgcn_mfma_f32_16x16x32_bf16(Bt[n][k], At[m][k], acc[ai][bj][m][n], 0, 0, 0); __builtin_amdgcn_s_setprio(0); } while (0)
; #define PG8_WAIT_L(n) asm volatile("s_waitcnt lgkmcnt(" #n ")" ::: "memory")
; #define PG8_BAR __builtin_amdgcn_s_barrier()
; #define PG8_SCHED __builtin_amdgcn_sched_barrier(0)
; template <class Epi>
; __device__ __forceinline__ void gemm_phase(LAS unsigned char* lds, const Gemm g, const StaticOrder& S, const Epi& E) {
;     ...
;             const bool last = (t == nt - 2);
;             const char* a1 = cA + (size_t)(t + 1) * kstep;
;             const char* a2 = last ? nA : cA + (size_t)(t + 2) * kstep; const char* b2 = last ? nB : cB + (size_t)(t + 2) * kstep;
;             const char* a3 = a2 + kstep; const char* b3 = b2 + kstep;
;             PG8_LDB(B0, 0, 0); PG8_SCHED; PG8_LDA(At, 0, 0); PG8_STAGE(PG8_SA(1, 1), a1 + hstepA, voffA);
;             PG8_WAIT_L(8); PG8_BAR; PG8_WAIT_L(0); PG8_MMA(0, 0, At, B0); PG8_BAR; PG8_SCHED;
;             PG8_LDB(B1, 0, 1); PG8_STAGE(PG8_SB(0, 0), b2, voffB);
;             PG8_BAR; PG8_WAIT_L(0); PG8_MMA(0, 1, At, B1); PG8_BAR;
;             PG8_LDA(At, 0, 1); PG8_STAGE(PG8_SA(0, 0), a2, voffA);
;             PG8_BAR; PG8_WAIT_L(0); PG8_MMA(1, 0, At, B0); PG8_BAR; PG8_SCHED;
.LBB0_187:
	s_add_i32 s54, s22, 2
	s_add_u32 s23, s4, 0x4000
	s_addc_u32 s24, s5, 0
	s_cmp_eq_u32 s40, s22
	s_cselect_b32 s26, s6, s23
	s_cselect_b32 s27, s7, s24
	s_cselect_b32 s24, s20, s50
	s_cselect_b32 s25, s21, s51
	s_add_u32 s22, s26, 0x4000
	s_addc_u32 s23, s27, 0
	s_add_i32 s55, 0, 0x10000
	v_add_u32_e32 v140, s55, v207
	ds_read_b128 v[128:131], v140
	ds_read_b128 v[132:135], v140 offset:1024
	ds_read_b128 v[136:139], v140 offset:2048
	ds_read_b128 v[140:143], v140 offset:3072
	v_lshl_add_u64 v[186:187], s[4:5], 0, v[158:159]
	s_add_i32 m0, s33, 0xc000
	ds_read_b128 v[144:147], v209
	ds_read_b128 v[148:151], v209 offset:1024
	ds_read_b128 v[162:165], v209 offset:2048
	ds_read_b128 v[166:169], v209 offset:3072
	ds_read_b128 v[170:173], v209 offset:4096
	ds_read_b128 v[174:177], v209 offset:5120
	ds_read_b128 v[178:181], v209 offset:6144
	ds_read_b128 v[182:185], v209 offset:7168
	global_load_lds_dwordx4 v[186:187], off
	s_add_i32 m0, s33, 0xe000
	v_lshl_add_u64 v[186:187], s[4:5], 0, v[160:161]
	global_load_lds_dwordx4 v[186:187], off
	s_waitcnt lgkmcnt(8)
	s_barrier
	s_waitcnt lgkmcnt(0)
	s_setprio 1
	v_mfma_f32_16x16x32_bf16 v[124:127], v[128:131], v[144:147], v[124:127]
	v_mfma_f32_16x16x32_bf16 v[120:123], v[136:139], v[144:147], v[120:123]
	v_mfma_f32_16x16x32_bf16 v[116:119], v[128:131], v[162:165], v[116:119]
	v_mfma_f32_16x16x32_bf16 v[112:115], v[136:139], v[162:165], v[112:115]
	v_mfma_f32_16x16x32_bf16 v[108:111], v[128:131], v[170:173], v[108:111]
	v_mfma_f32_16x16x32_bf16 v[104:107], v[136:139], v[170:173], v[104:107]
	v_mfma_f32_16x16x32_bf16 v[100:103], v[128:131], v[178:181], v[100:103]
	v_mfma_f32_16x16x32_bf16 v[96:99], v[136:139], v[178:181], v[96:99]
	v_mfma_f32_16x16x32_bf16 v[124:127], v[132:135], v[148:151], v[124:127]
	v_mfma_f32_16x16x32_bf16 v[120:123], v[140:143], v[148:151], v[120:123]
	v_mfma_f32_16x16x32_bf16 v[116:119], v[132:135], v[166:169], v[116:119]
	v_mfma_f32_16x16x32_bf16 v[112:115], v[140:143], v[166:169], v[112:115]
	v_mfma_f32_16x16x32_bf16 v[108:111], v[132:135], v[174:177], v[108:111]
	v_mfma_f32_16x16x32_bf16 v[104:107], v[140:143], v[174:177], v[104:107]
	v_mfma_f32_16x16x32_bf16 v[100:103], v[132:135], v[182:185], v[100:103]
	s_setprio 0
	v_mfma_f32_16x16x32_bf16 v[96:99], v[140:143], v[182:185], v[96:99]
	s_barrier
	s_add_i32 s58, 0, 0x14000
	s_add_i32 s55, s55, s31
	v_add_u32_e32 v198, s58, v207
	v_lshl_add_u64 v[202:203], s[24:25], 0, v[152:153]
	s_mov_b32 m0, s55
	ds_read_b128 v[186:189], v198
	ds_read_b128 v[190:193], v198 offset:1024
	ds_read_b128 v[194:197], v198 offset:2048
	ds_read_b128 v[198:201], v198 offset:3072
	global_load_lds_dwordx4 v[202:203], off
	s_add_i32 m0, s55, 0x2000
	v_lshl_add_u64 v[202:203], s[24:25], 0, v[156:157]
	global_load_lds_dwordx4 v[202:203], off
	s_barrier
	s_waitcnt lgkmcnt(0)
	s_setprio 1
	v_mfma_f32_16x16x32_bf16 v[92:95], v[186:189], v[144:147], v[92:95]
	v_mfma_f32_16x16x32_bf16 v[88:91], v[194:197], v[144:147], v[88:91]
	s_mov_b32 m0, s33
	v_lshl_add_u64 v[202:203], s[26:27], 0, v[152:153]
	v_mfma_f32_16x16x32_bf16 v[84:87], v[186:189], v[162:165], v[84:87]
	v_mfma_f32_16x16x32_bf16 v[80:83], v[194:197], v[162:165], v[80:83]
	v_mfma_f32_16x16x32_bf16 v[76:79], v[186:189], v[170:173], v[76:79]
	v_mfma_f32_16x16x32_bf16 v[72:75], v[194:197], v[170:173], v[72:75]
	v_mfma_f32_16x16x32_bf16 v[68:71], v[186:189], v[178:181], v[68:71]
	v_mfma_f32_16x16x32_bf16 v[64:67], v[194:197], v[178:181], v[64:67]
	v_mfma_f32_16x16x32_bf16 v[92:95], v[190:193], v[148:151], v[92:95]
	v_mfma_f32_16x16x32_bf16 v[88:91], v[198:201], v[148:151], v[88:91]
	v_mfma_f32_16x16x32_bf16 v[84:87], v[190:193], v[166:169], v[84:87]
	v_mfma_f32_16x16x32_bf16 v[80:83], v[198:201], v[166:169], v[80:83]
	v_mfma_f32_16x16x32_bf16 v[76:79], v[190:193], v[174:177], v[76:79]
	v_mfma_f32_16x16x32_bf16 v[72:75], v[198:201], v[174:177], v[72:75]
	v_mfma_f32_16x16x32_bf16 v[68:71], v[190:193], v[182:185], v[68:71]
	s_setprio 0
	v_mfma_f32_16x16x32_bf16 v[64:67], v[198:201], v[182:185], v[64:67]
	s_barrier
	ds_read_b128 v[144:147], v209 offset:16384
	ds_read_b128 v[148:151], v209 offset:17408
	ds_read_b128 v[162:165], v209 offset:18432
	ds_read_b128 v[166:169], v209 offset:19456
	ds_read_b128 v[170:173], v209 offset:20480
	ds_read_b128 v[174:177], v209 offset:21504
	ds_read_b128 v[178:181], v209 offset:22528
	ds_read_b128 v[182:185], v209 offset:23552
	global_load_lds_dwordx4 v[202:203], off
	s_mov_b32 m0, s34
	v_lshl_add_u64 v[202:203], s[26:27], 0, v[156:157]
	global_load_lds_dwordx4 v[202:203], off
	s_barrier
	s_waitcnt lgkmcnt(0)
	s_setprio 1
	v_mfma_f32_16x16x32_bf16 v[60:63], v[128:131], v[144:147], v[60:63]
	v_mfma_f32_16x16x32_bf16 v[56:59], v[136:139], v[144:147], v[56:59]
	v_mfma_f32_16x16x32_bf16 v[52:55], v[128:131], v[162:165], v[52:55]
	v_mfma_f32_16x16x32_bf16 v[48:51], v[136:139], v[162:165], v[48:51]
	v_mfma_f32_16x16x32_bf16 v[44:47], v[128:131], v[170:173], v[44:47]
	v_mfma_f32_16x16x32_bf16 v[40:43], v[136:139], v[170:173], v[40:43]
	v_mfma_f32_16x16x32_bf16 v[36:39], v[128:131], v[178:181], v[36:39]
	v_mfma_f32_16x16x32_bf16 v[32:35], v[136:139], v[178:181], v[32:35]
	v_mfma_f32_16x16x32_bf16 v[60:63], v[132:135], v[148:151], v[60:63]
	v_mfma_f32_16x16x32_bf16 v[56:59], v[140:143], v[148:151], v[56:59]
	v_mfma_f32_16x16x32_bf16 v[52:55], v[132:135], v[166:169], v[52:55]
	v_mfma_f32_16x16x32_bf16 v[48:51], v[140:143], v[166:169], v[48:51]
	v_mfma_f32_16x16x32_bf16 v[44:47], v[132:135], v[174:177], v[44:47]
	v_mfma_f32_16x16x32_bf16 v[40:43], v[140:143], v[174:177], v[40:43]
	v_mfma_f32_16x16x32_bf16 v[36:39], v[132:135], v[182:185], v[36:39]
	s_setprio 0
	v_mfma_f32_16x16x32_bf16 v[32:35], v[140:143], v[182:185], v[32:35]
	s_barrier
; #define PG8_STAGE(bufoff, gbase, voff) do { _Pragma("unroll") for (int _i = 0; _i < 2; ++_i) \
;         __builtin_amdgcn_global_load_lds((const unsigned*)((const char*)(gbase) + (voff)[_i]), (LAS unsigned*)(lds + (bufoff) + ldsw + _i * 8192), 16, 0, 0); } while (0)
; #define PG8_LDA(dst, b, h) do { _Pragma("unroll") for (int m = 0; m < 4; ++m) _Pragma("unroll") for (int k = 0; k < 2; ++k) dst[m][k] = *(const LAS bf16x8*)(lds + PG8_SA(b, h) + aoff + m * 2048 + k * 1024); } while (0)
; #define PG8_LDB(dst, b, h) do { _Pragma("unroll") for (int n = 0; n < 2; ++n) _Pragma("unroll") for (int k = 0; k < 2; ++k) dst[n][k] = *(const LAS bf16x8*)(lds + PG8_SB(b, h) + boff + n * 2048 + k * 1024); } while (0)
; #define PG8_MMA(ai, bj, At, Bt) do { __builtin_amdgcn_s_setprio(1); _Pragma("unroll") for (int m = 0; m < 4; ++m) _Pragma("unroll") for (int n = 0; n < 2; ++n) _Pragma("unroll") for (int k = 0; k < 2; ++k) \
;         acc[ai][bj][m][n] = __builtin_amdgcn_mfma_f32_16x16x32_bf16(Bt[n][k], At[m][k], acc[ai][bj][m][n], 0, 0, 0); __builtin_amdgcn_s_setprio(0); } while (0)
; #define PG8_WAIT_V(n) asm volatile("s_waitcnt vmcnt(" #n ")" ::: "memory")
; #define PG8_WAIT_L(n) asm volatile("s_waitcnt lgkmcnt(" #n ")" ::: "memory")
; #define PG8_BAR __builtin_amdgcn_s_barrier()
; #define PG8_SCHED __builtin_amdgcn_sched_barrier(0)
; template <class Epi>
; __device__ __forceinline__ void gemm_phase(LAS unsigned char* lds, const Gemm g, const StaticOrder& S, const Epi& E) {
;     ...
;             PG8_STAGE(PG8_SB(0, 1), b2 + hstepB, voffB);
;             PG8_WAIT_V(6); PG8_BAR; PG8_MMA(1, 1, At, B1); PG8_BAR;
;             PG8_LDB(B0, 1, 0); PG8_SCHED; PG8_LDA(At, 1, 0); PG8_STAGE(PG8_SA(0, 1), a2 + hstepA, voffA);
;             PG8_WAIT_L(8); PG8_BAR; PG8_WAIT_L(0); PG8_MMA(0, 0, At, B0); PG8_BAR; PG8_SCHED;
;             PG8_LDB(B1, 1, 1); PG8_STAGE(PG8_SB(1, 0), b3, voffB);
;             PG8_BAR; PG8_WAIT_L(0); PG8_MMA(0, 1, At, B1); PG8_BAR;
;             PG8_LDA(At, 1, 1); PG8_STAGE(PG8_SA(1, 0), a3, voffA);
;             PG8_BAR; PG8_WAIT_L(0); PG8_MMA(1, 0, At, B0); PG8_BAR; PG8_SCHED;
	s_add_u32 s56, s24, s52
	s_addc_u32 s57, s25, 0
	s_add_i32 s55, s58, s31
	s_mov_b32 m0, s55
	v_lshl_add_u64 v[128:129], s[56:57], 0, v[152:153]
	global_load_lds_dwordx4 v[128:129], off
	s_add_i32 m0, s55, 0x2000
	v_lshl_add_u64 v[128:129], s[56:57], 0, v[156:157]
	global_load_lds_dwordx4 v[128:129], off
	s_waitcnt vmcnt(6)
	s_barrier
	s_setprio 1
	v_mfma_f32_16x16x32_bf16 v[28:31], v[186:189], v[144:147], v[28:31]
	v_mfma_f32_16x16x32_bf16 v[24:27], v[194:197], v[144:147], v[24:27]
	s_add_i32 s55, 0, 0x18000
	v_add_u32_e32 v140, s55, v207
	v_mfma_f32_16x16x32_bf16 v[20:23], v[186:189], v[162:165], v[20:23]
	v_mfma_f32_16x16x32_bf16 v[16:19], v[194:197], v[162:165], v[16:19]
	v_mfma_f32_16x16x32_bf16 v[12:15], v[186:189], v[170:173], v[12:15]
	v_mfma_f32_16x16x32_bf16 v[8:11], v[194:197], v[170:173], v[8:11]
	v_mfma_f32_16x16x32_bf16 v[4:7], v[186:189], v[178:181], v[4:7]
	v_mfma_f32_16x16x32_bf16 v[0:3], v[194:197], v[178:181], v[0:3]
	v_mfma_f32_16x16x32_bf16 v[28:31], v[190:193], v[148:151], v[28:31]
	v_mfma_f32_16x16x32_bf16 v[24:27], v[198:201], v[148:151], v[24:27]
	v_mfma_f32_16x16x32_bf16 v[20:23], v[190:193], v[166:169], v[20:23]
	v_mfma_f32_16x16x32_bf16 v[16:19], v[198:201], v[166:169], v[16:19]
	v_mfma_f32_16x16x32_bf16 v[12:15], v[190:193], v[174:177], v[12:15]
	v_mfma_f32_16x16x32_bf16 v[8:11], v[198:201], v[174:177], v[8:11]
	v_mfma_f32_16x16x32_bf16 v[4:7], v[190:193], v[182:185], v[4:7]
	s_setprio 0
	v_mfma_f32_16x16x32_bf16 v[0:3], v[198:201], v[182:185], v[0:3]
	s_barrier
	ds_read_b128 v[128:131], v140
	ds_read_b128 v[132:135], v140 offset:1024
	ds_read_b128 v[136:139], v140 offset:2048
	ds_read_b128 v[140:143], v140 offset:3072
	s_add_u32 s26, s26, s52
	s_addc_u32 s27, s27, 0
	s_mov_b32 m0, s35
	v_lshl_add_u64 v[186:187], s[26:27], 0, v[152:153]
	ds_read_b128 v[144:147], v209 offset:32768
	ds_read_b128 v[148:151], v209 offset:33792
	ds_read_b128 v[162:165], v209 offset:34816
	ds_read_b128 v[166:169], v209 offset:35840
	ds_read_b128 v[170:173], v209 offset:36864
	ds_read_b128 v[174:177], v209 offset:37888
	ds_read_b128 v[178:181], v209 offset:38912
	ds_read_b128 v[182:185], v209 offset:39936
	global_load_lds_dwordx4 v[186:187], off
	s_mov_b32 m0, s36
	v_lshl_add_u64 v[186:187], s[26:27], 0, v[156:157]
	global_load_lds_dwordx4 v[186:187], off
	s_waitcnt lgkmcnt(8)
	s_barrier
	s_waitcnt lgkmcnt(0)
	s_setprio 1
	v_mfma_f32_16x16x32_bf16 v[124:127], v[128:131], v[144:147], v[124:127]
	v_mfma_f32_16x16x32_bf16 v[120:123], v[136:139], v[144:147], v[120:123]
	v_mfma_f32_16x16x32_bf16 v[116:119], v[128:131], v[162:165], v[116:119]
	v_mfma_f32_16x16x32_bf16 v[112:115], v[136:139], v[162:165], v[112:115]
	v_mfma_f32_16x16x32_bf16 v[108:111], v[128:131], v[170:173], v[108:111]
	v_mfma_f32_16x16x32_bf16 v[104:107], v[136:139], v[170:173], v[104:107]
	v_mfma_f32_16x16x32_bf16 v[100:103], v[128:131], v[178:181], v[100:103]
	v_mfma_f32_16x16x32_bf16 v[96:99], v[136:139], v[178:181], v[96:99]
	v_mfma_f32_16x16x32_bf16 v[124:127], v[132:135], v[148:151], v[124:127]
	v_mfma_f32_16x16x32_bf16 v[120:123], v[140:143], v[148:151], v[120:123]
	v_mfma_f32_16x16x32_bf16 v[116:119], v[132:135], v[166:169], v[116:119]
	v_mfma_f32_16x16x32_bf16 v[112:115], v[140:143], v[166:169], v[112:115]
	v_mfma_f32_16x16x32_bf16 v[108:111], v[132:135], v[174:177], v[108:111]
	v_mfma_f32_16x16x32_bf16 v[104:107], v[140:143], v[174:177], v[104:107]
	v_mfma_f32_16x16x32_bf16 v[100:103], v[132:135], v[182:185], v[100:103]
	s_setprio 0
	v_mfma_f32_16x16x32_bf16 v[96:99], v[140:143], v[182:185], v[96:99]
	s_barrier
	s_add_i32 s26, 0, 0x1c000
	s_add_u32 s24, s24, 0x4000
	s_addc_u32 s25, s25, 0
	s_add_i32 s27, s55, s31
	v_add_u32_e32 v198, s26, v207
	v_lshl_add_u64 v[202:203], s[24:25], 0, v[152:153]
	s_mov_b32 m0, s27
	ds_read_b128 v[186:189], v198
	ds_read_b128 v[190:193], v198 offset:1024
	ds_read_b128 v[194:197], v198 offset:2048
	ds_read_b128 v[198:201], v198 offset:3072
	global_load_lds_dwordx4 v[202:203], off
	s_add_i32 m0, s27, 0x2000
	v_lshl_add_u64 v[202:203], s[24:25], 0, v[156:157]
	global_load_lds_dwordx4 v[202:203], off
	s_barrier
; #define PG8_STAGE(bufoff, gbase, voff) do { _Pragma("unroll") for (int _i = 0; _i < 2; ++_i) \
;         __builtin_amdgcn_global_load_lds((const unsigned*)((const char*)(gbase) + (voff)[_i]), (LAS unsigned*)(lds + (bufoff) + ldsw + _i * 8192), 16, 0, 0); } while (0)
; #define PG8_MMA(ai, bj, At, Bt) do { __builtin_amdgcn_s_setprio(1); _Pragma("unroll") for (int m = 0; m < 4; ++m) _Pragma("unroll") for (int n = 0; n < 2; ++n) _Pragma("unroll") for (int k = 0; k < 2; ++k) \
;         acc[ai][bj][m][n] = __builtin_amdgcn_mfma_f32_16x16x32_bf16(Bt[n][k], At[m][k], acc[ai][bj][m][n], 0, 0, 0); __builtin_amdgcn_s_setprio(0); } while (0)
; #define PG8_WAIT_V(n) asm volatile("s_waitcnt vmcnt(" #n ")" ::: "memory")
; #define PG8_WAIT_L(n) asm volatile("s_waitcnt lgkmcnt(" #n ")" ::: "memory")
; #define PG8_BAR __builtin_amdgcn_s_barrier()
; #define PG8_SCHED __builtin_amdgcn_sched_barrier(0)
; template <class Epi>
; __device__ __forceinline__ void gemm_phase(LAS unsigned char* lds, const Gemm g, const StaticOrder& S, const Epi& E) {
;     ...
;             PG8_BAR; PG8_WAIT_L(0); PG8_MMA(1, 0, At, B0); PG8_BAR; PG8_SCHED;
;             PG8_STAGE(PG8_SB(1, 1), b3 + hstepB, voffB);
;             PG8_WAIT_V(6); PG8_BAR; PG8_MMA(1, 1, At, B1); PG8_BAR;
;     __device__ __forceinline__ void operator()(const f32x4 (&acc)[2][2][4][2], const Unit& u, int wr, int wc, int fr, int fq) const {
;         const int row0 = u.pm * BM + wr * 64 + fr, col0 = u.pn * BM + wc * 32 + 8 * fq;
;         const float* gb = gate + (size_t)(row0 >> 12) * (6 * DM);
;         const bool ln = stats != nullptr;
;         constexpr int GB[4] = {0, 4, 8, 16};
;         f32x2 st[4];
; #pragma unroll
;         for (int grp = 0; grp < 3; ++grp) {
;             u32x4 xv[8]; f32x4 cg[2][2], cl[2][2], cb[2][2];
;             if (grp == 0 || grp == 2) {
; #pragma unroll
;                 for (int m = 0; m < 4; ++m) st[m] = ln ? *(const f32x2*)(stats + 2 * (row0 + (grp ? HALF : 0) + m * 16)) : (f32x2){0.f, 1.f};
	s_waitcnt lgkmcnt(0)
	s_setprio 1
	v_mfma_f32_16x16x32_bf16 v[92:95], v[186:189], v[144:147], v[92:95]
	v_mfma_f32_16x16x32_bf16 v[88:91], v[194:197], v[144:147], v[88:91]
	s_mov_b32 m0, s38
	v_lshl_add_u64 v[202:203], s[22:23], 0, v[152:153]
	v_mfma_f32_16x16x32_bf16 v[84:87], v[186:189], v[162:165], v[84:87]
	v_mfma_f32_16x16x32_bf16 v[80:83], v[194:197], v[162:165], v[80:83]
	v_mfma_f32_16x16x32_bf16 v[76:79], v[186:189], v[170:173], v[76:79]
	v_mfma_f32_16x16x32_bf16 v[72:75], v[194:197], v[170:173], v[72:75]
	v_mfma_f32_16x16x32_bf16 v[68:71], v[186:189], v[178:181], v[68:71]
	v_mfma_f32_16x16x32_bf16 v[64:67], v[194:197], v[178:181], v[64:67]
	v_mfma_f32_16x16x32_bf16 v[92:95], v[190:193], v[148:151], v[92:95]
	v_mfma_f32_16x16x32_bf16 v[88:91], v[198:201], v[148:151], v[88:91]
	v_mfma_f32_16x16x32_bf16 v[84:87], v[190:193], v[166:169], v[84:87]
	v_mfma_f32_16x16x32_bf16 v[80:83], v[198:201], v[166:169], v[80:83]
	v_mfma_f32_16x16x32_bf16 v[76:79], v[190:193], v[174:177], v[76:79]
	v_mfma_f32_16x16x32_bf16 v[72:75], v[198:201], v[174:177], v[72:75]
	v_mfma_f32_16x16x32_bf16 v[68:71], v[190:193], v[182:185], v[68:71]
	s_setprio 0
	v_mfma_f32_16x16x32_bf16 v[64:67], v[198:201], v[182:185], v[64:67]
	s_barrier
	ds_read_b128 v[144:147], v209 offset:49152
	ds_read_b128 v[148:151], v209 offset:50176
	ds_read_b128 v[162:165], v209 offset:51200
	ds_read_b128 v[166:169], v209 offset:52224
	ds_read_b128 v[170:173], v209 offset:53248
	ds_read_b128 v[174:177], v209 offset:54272
	ds_read_b128 v[178:181], v209 offset:55296
	ds_read_b128 v[182:185], v209 offset:56320
	global_load_lds_dwordx4 v[202:203], off
	s_mov_b32 m0, s39
	v_lshl_add_u64 v[202:203], s[22:23], 0, v[156:157]
	global_load_lds_dwordx4 v[202:203], off
	s_barrier
	s_waitcnt lgkmcnt(0)
	s_setprio 1
	v_mfma_f32_16x16x32_bf16 v[60:63], v[128:131], v[144:147], v[60:63]
	v_mfma_f32_16x16x32_bf16 v[56:59], v[136:139], v[144:147], v[56:59]
	v_mfma_f32_16x16x32_bf16 v[52:55], v[128:131], v[162:165], v[52:55]
	v_mfma_f32_16x16x32_bf16 v[48:51], v[136:139], v[162:165], v[48:51]
	v_mfma_f32_16x16x32_bf16 v[44:47], v[128:131], v[170:173], v[44:47]
	v_mfma_f32_16x16x32_bf16 v[40:43], v[136:139], v[170:173], v[40:43]
	v_mfma_f32_16x16x32_bf16 v[36:39], v[128:131], v[178:181], v[36:39]
	v_mfma_f32_16x16x32_bf16 v[32:35], v[136:139], v[178:181], v[32:35]
	v_mfma_f32_16x16x32_bf16 v[60:63], v[132:135], v[148:151], v[60:63]
	v_mfma_f32_16x16x32_bf16 v[56:59], v[140:143], v[148:151], v[56:59]
	v_mfma_f32_16x16x32_bf16 v[52:55], v[132:135], v[166:169], v[52:55]
	v_mfma_f32_16x16x32_bf16 v[48:51], v[140:143], v[166:169], v[48:51]
	v_mfma_f32_16x16x32_bf16 v[44:47], v[132:135], v[174:177], v[44:47]
	v_mfma_f32_16x16x32_bf16 v[40:43], v[140:143], v[174:177], v[40:43]
	v_mfma_f32_16x16x32_bf16 v[36:39], v[132:135], v[182:185], v[36:39]
	s_setprio 0
	v_mfma_f32_16x16x32_bf16 v[32:35], v[140:143], v[182:185], v[32:35]
	s_barrier
	s_add_u32 s22, s24, s52
	s_addc_u32 s23, s25, 0
	s_add_i32 s24, s26, s31
	s_mov_b32 m0, s24
	v_lshl_add_u64 v[128:129], s[22:23], 0, v[152:153]
	global_load_lds_dwordx4 v[128:129], off
	s_add_i32 m0, s24, 0x2000
	v_lshl_add_u64 v[128:129], s[22:23], 0, v[156:157]
	global_load_lds_dwordx4 v[128:129], off
	s_waitcnt vmcnt(6)
	s_barrier
	s_setprio 1
	v_mfma_f32_16x16x32_bf16 v[28:31], v[186:189], v[144:147], v[28:31]
	v_mfma_f32_16x16x32_bf16 v[24:27], v[194:197], v[144:147], v[24:27]
	s_add_u32 s4, s4, 0x8000
	s_addc_u32 s5, s5, 0
	s_add_u32 s50, s50, 0x8000
	s_addc_u32 s51, s51, 0
	v_mfma_f32_16x16x32_bf16 v[20:23], v[186:189], v[162:165], v[20:23]
	v_mfma_f32_16x16x32_bf16 v[16:19], v[194:197], v[162:165], v[16:19]
	v_mfma_f32_16x16x32_bf16 v[12:15], v[186:189], v[170:173], v[12:15]
	v_mfma_f32_16x16x32_bf16 v[8:11], v[194:197], v[170:173], v[8:11]
	v_mfma_f32_16x16x32_bf16 v[4:7], v[186:189], v[178:181], v[4:7]
	v_mfma_f32_16x16x32_bf16 v[0:3], v[194:197], v[178:181], v[0:3]
	v_mfma_f32_16x16x32_bf16 v[28:31], v[190:193], v[148:151], v[28:31]
	v_mfma_f32_16x16x32_bf16 v[24:27], v[198:201], v[148:151], v[24:27]
	v_mfma_f32_16x16x32_bf16 v[20:23], v[190:193], v[166:169], v[20:23]
	v_mfma_f32_16x16x32_bf16 v[16:19], v[198:201], v[166:169], v[16:19]
	v_mfma_f32_16x16x32_bf16 v[12:15], v[190:193], v[174:177], v[12:15]
	v_mfma_f32_16x16x32_bf16 v[8:11], v[198:201], v[174:177], v[8:11]
	v_mfma_f32_16x16x32_bf16 v[4:7], v[190:193], v[182:185], v[4:7]
	s_cmp_ge_u32 s54, s28
	s_mov_b32 s22, s54
	s_setprio 0
	v_mfma_f32_16x16x32_bf16 v[0:3], v[198:201], v[182:185], v[0:3]
	s_barrier
	s_cbranch_scc0 .LBB0_187
	s_lshl_b32 s22, s49, 8
	s_add_i32 s22, s22, s37
	v_or_b32_e32 v162, s22, v206
	v_lshlrev_b32_e32 v170, 1, v162
	v_cndmask_b32_e64 v128, 0, 1, s[12:13]
	v_mov_b32_e32 v182, 1.0
	v_mov_b32_e32 v184, 0
	v_cmp_ne_u32_e64 s[4:5], 1, v128
	s_andn2_b64 vcc, exec, s[12:13]
	v_ashrrev_i32_e32 v171, 31, v170
	v_mov_b32_e32 v192, 0
	v_mov_b32_e32 v194, 1.0
	s_cbranch_vccnz .LBB0_190
	v_lshl_add_u64 v[128:129], v[170:171], 2, s[14:15]
	global_load_dwordx2 v[192:193], v[128:129], off
	s_waitcnt vmcnt(0)
	v_mov_b32_e32 v194, v193

; #define PG8_STAGE(bufoff, gbase, voff) do { _Pragma("unroll") for (int _i = 0; _i < 2; ++_i) \
;         __builtin_amdgcn_global_load_lds((const unsigned*)((const char*)(gbase) + (voff)[_i]), (LAS unsigned*)(lds + (bufoff) + ldsw + _i * 8192), 16, 0, 0); } while (0)
; #define PG8_LDA(dst, b, h) do { _Pragma("unroll") for (int m = 0; m < 4; ++m) _Pragma("unroll") for (int k = 0; k < 2; ++k) dst[m][k] = *(const LAS bf16x8*)(lds + PG8_SA(b, h) + aoff + m * 2048 + k * 1024); } while (0)
; #define PG8_LDB(dst, b, h) do { _Pragma("unroll") for (int n = 0; n < 2; ++n) _Pragma("unroll") for (int k = 0; k < 2; ++k) dst[n][k] = *(const LAS bf16x8*)(lds + PG8_SB(b, h) + boff + n * 2048 + k * 1024); } while (0)
; #define PG8_MMA(ai, bj, At, Bt) do { __builtin_amdgcn_s_setprio(1); _Pragma("unroll") for (int m = 0; m < 4; ++m) _Pragma("unroll") for (int n = 0; n < 2; ++n) _Pragma("unroll") for (int k = 0; k < 2; ++k) \
;         acc[ai][bj][m][n] = __builtin_amdgcn_mfma_f32_16x16x32_bf16(Bt[n][k], At[m][k], acc[ai][bj][m][n], 0, 0, 0); __builtin_amdgcn_s_setprio(0); } while (0)
; #define PG8_WAIT_L(n) asm volatile("s_waitcnt lgkmcnt(" #n ")" ::: "memory")
; #define PG8_BAR __builtin_amdgcn_s_barrier()
; #define PG8_SCHED __builtin_amdgcn_sched_barrier(0)
; template <class Epi>
; __device__ __forceinline__ void gemm_phase(LAS unsigned char* lds, const Gemm g, const StaticOrder& S, const Epi& E) {
;     ...
;             const bool last = (t == nt - 2);
;             const char* a1 = cA + (size_t)(t + 1) * kstep;
;             const char* a2 = last ? nA : cA + (size_t)(t + 2) * kstep; const char* b2 = last ? nB : cB + (size_t)(t + 2) * kstep;
;             const char* a3 = a2 + kstep; const char* b3 = b2 + kstep;
;             PG8_LDB(B0, 0, 0); PG8_SCHED; PG8_LDA(At, 0, 0); PG8_STAGE(PG8_SA(1, 1), a1 + hstepA, voffA);
;             PG8_WAIT_L(8); PG8_BAR; PG8_WAIT_L(0); PG8_MMA(0, 0, At, B0); PG8_BAR; PG8_SCHED;
;             PG8_LDB(B1, 0, 1); PG8_STAGE(PG8_SB(0, 0), b2, voffB);
;             PG8_BAR; PG8_WAIT_L(0); PG8_MMA(0, 1, At, B1); PG8_BAR;
;             PG8_LDA(At, 0, 1); PG8_STAGE(PG8_SA(0, 0), a2, voffA);
;             PG8_BAR; PG8_WAIT_L(0); PG8_MMA(1, 0, At, B0); PG8_BAR; PG8_SCHED;
.LBB0_247:
	s_add_u32 s14, s12, 0xfff84000
	s_addc_u32 s15, s13, -1
	s_cmp_eq_u32 s38, 28
	s_cselect_b32 s18, s11, s14
	s_cselect_b32 s19, s5, s15
	s_cselect_b32 s14, s35, s36
	s_cselect_b32 s15, s3, s37
	s_add_u32 s16, s18, 0x4000
	s_addc_u32 s17, s19, 0
	s_add_i32 s39, 0, 0x10000
	v_add_u32_e32 v140, s39, v170
	ds_read_b128 v[128:131], v140
	ds_read_b128 v[132:135], v140 offset:1024
	ds_read_b128 v[136:139], v140 offset:2048
	ds_read_b128 v[140:143], v140 offset:3072
	v_lshl_add_u64 v[194:195], s[12:13], 0, v[156:157]
	s_add_i32 m0, s25, 0xc000
	ds_read_b128 v[144:147], v172
	ds_read_b128 v[148:151], v172 offset:1024
	ds_read_b128 v[166:169], v172 offset:2048
	ds_read_b128 v[174:177], v172 offset:3072
	ds_read_b128 v[178:181], v172 offset:4096
	ds_read_b128 v[182:185], v172 offset:5120
	ds_read_b128 v[186:189], v172 offset:6144
	ds_read_b128 v[190:193], v172 offset:7168
	global_load_lds_dwordx4 v[194:195], off
	s_add_i32 m0, s25, 0xe000
	v_lshl_add_u64 v[194:195], s[12:13], 0, v[158:159]
	global_load_lds_dwordx4 v[194:195], off
	s_waitcnt lgkmcnt(8)
	s_barrier
	s_waitcnt lgkmcnt(0)
	s_setprio 1
	v_mfma_f32_16x16x32_bf16 v[124:127], v[128:131], v[144:147], v[124:127]
	v_mfma_f32_16x16x32_bf16 v[120:123], v[136:139], v[144:147], v[120:123]
	v_mfma_f32_16x16x32_bf16 v[108:111], v[128:131], v[166:169], v[108:111]
	v_mfma_f32_16x16x32_bf16 v[104:107], v[136:139], v[166:169], v[104:107]
	v_mfma_f32_16x16x32_bf16 v[92:95], v[128:131], v[178:181], v[92:95]
	v_mfma_f32_16x16x32_bf16 v[88:91], v[136:139], v[178:181], v[88:91]
	v_mfma_f32_16x16x32_bf16 v[76:79], v[128:131], v[186:189], v[76:79]
	v_mfma_f32_16x16x32_bf16 v[72:75], v[136:139], v[186:189], v[72:75]
	v_mfma_f32_16x16x32_bf16 v[124:127], v[132:135], v[148:151], v[124:127]
	v_mfma_f32_16x16x32_bf16 v[120:123], v[140:143], v[148:151], v[120:123]
	v_mfma_f32_16x16x32_bf16 v[108:111], v[132:135], v[174:177], v[108:111]
	v_mfma_f32_16x16x32_bf16 v[104:107], v[140:143], v[174:177], v[104:107]
	v_mfma_f32_16x16x32_bf16 v[92:95], v[132:135], v[182:185], v[92:95]
	v_mfma_f32_16x16x32_bf16 v[88:91], v[140:143], v[182:185], v[88:91]
	v_mfma_f32_16x16x32_bf16 v[76:79], v[132:135], v[190:193], v[76:79]
	s_setprio 0
	v_mfma_f32_16x16x32_bf16 v[72:75], v[140:143], v[190:193], v[72:75]
	s_barrier
	s_add_i32 s42, 0, 0x14000
	s_add_i32 s39, s39, s23
	v_add_u32_e32 v152, s42, v170
	v_lshl_add_u64 v[210:211], s[14:15], 0, v[156:157]
	s_mov_b32 m0, s39
	ds_read_b128 v[194:197], v152
	ds_read_b128 v[198:201], v152 offset:1024
	ds_read_b128 v[202:205], v152 offset:2048
	ds_read_b128 v[206:209], v152 offset:3072
	global_load_lds_dwordx4 v[210:211], off
	s_add_i32 m0, s39, 0x2000
	v_lshl_add_u64 v[210:211], s[14:15], 0, v[158:159]
	global_load_lds_dwordx4 v[210:211], off
	s_barrier
	s_waitcnt lgkmcnt(0)
	s_setprio 1
	v_mfma_f32_16x16x32_bf16 v[116:119], v[194:197], v[144:147], v[116:119]
	v_mfma_f32_16x16x32_bf16 v[112:115], v[202:205], v[144:147], v[112:115]
	s_mov_b32 m0, s25
	v_lshl_add_u64 v[210:211], s[18:19], 0, v[156:157]
	v_mfma_f32_16x16x32_bf16 v[100:103], v[194:197], v[166:169], v[100:103]
	v_mfma_f32_16x16x32_bf16 v[96:99], v[202:205], v[166:169], v[96:99]
	v_mfma_f32_16x16x32_bf16 v[84:87], v[194:197], v[178:181], v[84:87]
	v_mfma_f32_16x16x32_bf16 v[80:83], v[202:205], v[178:181], v[80:83]
	v_mfma_f32_16x16x32_bf16 v[68:71], v[194:197], v[186:189], v[68:71]
	v_mfma_f32_16x16x32_bf16 v[64:67], v[202:205], v[186:189], v[64:67]
	v_mfma_f32_16x16x32_bf16 v[116:119], v[198:201], v[148:151], v[116:119]
	v_mfma_f32_16x16x32_bf16 v[112:115], v[206:209], v[148:151], v[112:115]
	v_mfma_f32_16x16x32_bf16 v[100:103], v[198:201], v[174:177], v[100:103]
	v_mfma_f32_16x16x32_bf16 v[96:99], v[206:209], v[174:177], v[96:99]
	v_mfma_f32_16x16x32_bf16 v[84:87], v[198:201], v[182:185], v[84:87]
	v_mfma_f32_16x16x32_bf16 v[80:83], v[206:209], v[182:185], v[80:83]
	v_mfma_f32_16x16x32_bf16 v[68:71], v[198:201], v[190:193], v[68:71]
	s_setprio 0
	v_mfma_f32_16x16x32_bf16 v[64:67], v[206:209], v[190:193], v[64:67]
	s_barrier
	ds_read_b128 v[144:147], v172 offset:16384
	ds_read_b128 v[148:151], v172 offset:17408
	ds_read_b128 v[166:169], v172 offset:18432
	ds_read_b128 v[174:177], v172 offset:19456
	ds_read_b128 v[178:181], v172 offset:20480
	ds_read_b128 v[182:185], v172 offset:21504
	ds_read_b128 v[186:189], v172 offset:22528
	ds_read_b128 v[190:193], v172 offset:23552
	global_load_lds_dwordx4 v[210:211], off
	s_mov_b32 m0, s26
	v_lshl_add_u64 v[210:211], s[18:19], 0, v[158:159]
	global_load_lds_dwordx4 v[210:211], off
	s_barrier
	s_waitcnt lgkmcnt(0)
	s_setprio 1
	v_mfma_f32_16x16x32_bf16 v[60:63], v[128:131], v[144:147], v[60:63]
	v_mfma_f32_16x16x32_bf16 v[56:59], v[136:139], v[144:147], v[56:59]
	v_mfma_f32_16x16x32_bf16 v[44:47], v[128:131], v[166:169], v[44:47]
	v_mfma_f32_16x16x32_bf16 v[40:43], v[136:139], v[166:169], v[40:43]
	v_mfma_f32_16x16x32_bf16 v[28:31], v[128:131], v[178:181], v[28:31]
	v_mfma_f32_16x16x32_bf16 v[24:27], v[136:139], v[178:181], v[24:27]
	v_mfma_f32_16x16x32_bf16 v[12:15], v[128:131], v[186:189], v[12:15]
	v_mfma_f32_16x16x32_bf16 v[8:11], v[136:139], v[186:189], v[8:11]
	v_mfma_f32_16x16x32_bf16 v[60:63], v[132:135], v[148:151], v[60:63]
	v_mfma_f32_16x16x32_bf16 v[56:59], v[140:143], v[148:151], v[56:59]
	v_mfma_f32_16x16x32_bf16 v[44:47], v[132:135], v[174:177], v[44:47]
	v_mfma_f32_16x16x32_bf16 v[40:43], v[140:143], v[174:177], v[40:43]
	v_mfma_f32_16x16x32_bf16 v[28:31], v[132:135], v[182:185], v[28:31]
	v_mfma_f32_16x16x32_bf16 v[24:27], v[140:143], v[182:185], v[24:27]
	v_mfma_f32_16x16x32_bf16 v[12:15], v[132:135], v[190:193], v[12:15]
	s_setprio 0
	v_mfma_f32_16x16x32_bf16 v[8:11], v[140:143], v[190:193], v[8:11]
	s_barrier
; #define PG8_STAGE(bufoff, gbase, voff) do { _Pragma("unroll") for (int _i = 0; _i < 2; ++_i) \
;         __builtin_amdgcn_global_load_lds((const unsigned*)((const char*)(gbase) + (voff)[_i]), (LAS unsigned*)(lds + (bufoff) + ldsw + _i * 8192), 16, 0, 0); } while (0)
; #define PG8_LDA(dst, b, h) do { _Pragma("unroll") for (int m = 0; m < 4; ++m) _Pragma("unroll") for (int k = 0; k < 2; ++k) dst[m][k] = *(const LAS bf16x8*)(lds + PG8_SA(b, h) + aoff + m * 2048 + k * 1024); } while (0)
; #define PG8_LDB(dst, b, h) do { _Pragma("unroll") for (int n = 0; n < 2; ++n) _Pragma("unroll") for (int k = 0; k < 2; ++k) dst[n][k] = *(const LAS bf16x8*)(lds + PG8_SB(b, h) + boff + n * 2048 + k * 1024); } while (0)
; #define PG8_MMA(ai, bj, At, Bt) do { __builtin_amdgcn_s_setprio(1); _Pragma("unroll") for (int m = 0; m < 4; ++m) _Pragma("unroll") for (int n = 0; n < 2; ++n) _Pragma("unroll") for (int k = 0; k < 2; ++k) \
;         acc[ai][bj][m][n] = __builtin_amdgcn_mfma_f32_16x16x32_bf16(Bt[n][k], At[m][k], acc[ai][bj][m][n], 0, 0, 0); __builtin_amdgcn_s_setprio(0); } while (0)
; #define PG8_WAIT_V(n) asm volatile("s_waitcnt vmcnt(" #n ")" ::: "memory")
; #define PG8_WAIT_L(n) asm volatile("s_waitcnt lgkmcnt(" #n ")" ::: "memory")
; #define PG8_BAR __builtin_amdgcn_s_barrier()
; #define PG8_SCHED __builtin_amdgcn_sched_barrier(0)
; template <class Epi>
; __device__ __forceinline__ void gemm_phase(LAS unsigned char* lds, const Gemm g, const StaticOrder& S, const Epi& E) {
;     ...
;             PG8_STAGE(PG8_SB(0, 1), b2 + hstepB, voffB);
;             PG8_WAIT_V(6); PG8_BAR; PG8_MMA(1, 1, At, B1); PG8_BAR;
;             PG8_LDB(B0, 1, 0); PG8_SCHED; PG8_LDA(At, 1, 0); PG8_STAGE(PG8_SA(0, 1), a2 + hstepA, voffA);
;             PG8_WAIT_L(8); PG8_BAR; PG8_WAIT_L(0); PG8_MMA(0, 0, At, B0); PG8_BAR; PG8_SCHED;
;             PG8_LDB(B1, 1, 1); PG8_STAGE(PG8_SB(1, 0), b3, voffB);
;             PG8_BAR; PG8_WAIT_L(0); PG8_MMA(0, 1, At, B1); PG8_BAR;
;             PG8_LDA(At, 1, 1); PG8_STAGE(PG8_SA(1, 0), a3, voffA);
;             PG8_BAR; PG8_WAIT_L(0); PG8_MMA(1, 0, At, B0); PG8_BAR; PG8_SCHED;
	s_add_u32 s40, s14, 0x80000
	s_addc_u32 s41, s15, 0
	s_add_i32 s39, s42, s23
	s_mov_b32 m0, s39
	v_lshl_add_u64 v[128:129], s[40:41], 0, v[156:157]
	global_load_lds_dwordx4 v[128:129], off
	s_add_i32 m0, s39, 0x2000
	v_lshl_add_u64 v[128:129], s[40:41], 0, v[158:159]
	global_load_lds_dwordx4 v[128:129], off
	s_waitcnt vmcnt(6)
	s_barrier
	s_setprio 1
	v_mfma_f32_16x16x32_bf16 v[52:55], v[194:197], v[144:147], v[52:55]
	v_mfma_f32_16x16x32_bf16 v[48:51], v[202:205], v[144:147], v[48:51]
	s_add_i32 s39, 0, 0x18000
	v_add_u32_e32 v140, s39, v170
	v_mfma_f32_16x16x32_bf16 v[36:39], v[194:197], v[166:169], v[36:39]
	v_mfma_f32_16x16x32_bf16 v[32:35], v[202:205], v[166:169], v[32:35]
	v_mfma_f32_16x16x32_bf16 v[20:23], v[194:197], v[178:181], v[20:23]
	v_mfma_f32_16x16x32_bf16 v[16:19], v[202:205], v[178:181], v[16:19]
	v_mfma_f32_16x16x32_bf16 v[4:7], v[194:197], v[186:189], v[4:7]
	v_mfma_f32_16x16x32_bf16 v[0:3], v[202:205], v[186:189], v[0:3]
	v_mfma_f32_16x16x32_bf16 v[52:55], v[198:201], v[148:151], v[52:55]
	v_mfma_f32_16x16x32_bf16 v[48:51], v[206:209], v[148:151], v[48:51]
	v_mfma_f32_16x16x32_bf16 v[36:39], v[198:201], v[174:177], v[36:39]
	v_mfma_f32_16x16x32_bf16 v[32:35], v[206:209], v[174:177], v[32:35]
	v_mfma_f32_16x16x32_bf16 v[20:23], v[198:201], v[182:185], v[20:23]
	v_mfma_f32_16x16x32_bf16 v[16:19], v[206:209], v[182:185], v[16:19]
	v_mfma_f32_16x16x32_bf16 v[4:7], v[198:201], v[190:193], v[4:7]
	s_setprio 0
	v_mfma_f32_16x16x32_bf16 v[0:3], v[206:209], v[190:193], v[0:3]
	s_barrier
	ds_read_b128 v[128:131], v140
	ds_read_b128 v[132:135], v140 offset:1024
	ds_read_b128 v[136:139], v140 offset:2048
	ds_read_b128 v[140:143], v140 offset:3072
	s_add_u32 s18, s18, 0x80000
	s_addc_u32 s19, s19, 0
	s_mov_b32 m0, s27
	v_lshl_add_u64 v[194:195], s[18:19], 0, v[156:157]
	ds_read_b128 v[144:147], v172 offset:32768
	ds_read_b128 v[148:151], v172 offset:33792
	ds_read_b128 v[166:169], v172 offset:34816
	ds_read_b128 v[174:177], v172 offset:35840
	ds_read_b128 v[178:181], v172 offset:36864
	ds_read_b128 v[182:185], v172 offset:37888
	ds_read_b128 v[186:189], v172 offset:38912
	ds_read_b128 v[190:193], v172 offset:39936
	global_load_lds_dwordx4 v[194:195], off
	s_mov_b32 m0, s28
	v_lshl_add_u64 v[194:195], s[18:19], 0, v[158:159]
	global_load_lds_dwordx4 v[194:195], off
	s_waitcnt lgkmcnt(8)
	s_barrier
	s_waitcnt lgkmcnt(0)
	s_setprio 1
	v_mfma_f32_16x16x32_bf16 v[124:127], v[128:131], v[144:147], v[124:127]
	v_mfma_f32_16x16x32_bf16 v[120:123], v[136:139], v[144:147], v[120:123]
	v_mfma_f32_16x16x32_bf16 v[108:111], v[128:131], v[166:169], v[108:111]
	v_mfma_f32_16x16x32_bf16 v[104:107], v[136:139], v[166:169], v[104:107]
	v_mfma_f32_16x16x32_bf16 v[92:95], v[128:131], v[178:181], v[92:95]
	v_mfma_f32_16x16x32_bf16 v[88:91], v[136:139], v[178:181], v[88:91]
	v_mfma_f32_16x16x32_bf16 v[76:79], v[128:131], v[186:189], v[76:79]
	v_mfma_f32_16x16x32_bf16 v[72:75], v[136:139], v[186:189], v[72:75]
	v_mfma_f32_16x16x32_bf16 v[124:127], v[132:135], v[148:151], v[124:127]
	v_mfma_f32_16x16x32_bf16 v[120:123], v[140:143], v[148:151], v[120:123]
	v_mfma_f32_16x16x32_bf16 v[108:111], v[132:135], v[174:177], v[108:111]
	v_mfma_f32_16x16x32_bf16 v[104:107], v[140:143], v[174:177], v[104:107]
	v_mfma_f32_16x16x32_bf16 v[92:95], v[132:135], v[182:185], v[92:95]
	v_mfma_f32_16x16x32_bf16 v[88:91], v[140:143], v[182:185], v[88:91]
	v_mfma_f32_16x16x32_bf16 v[76:79], v[132:135], v[190:193], v[76:79]
	s_setprio 0
	v_mfma_f32_16x16x32_bf16 v[72:75], v[140:143], v[190:193], v[72:75]
	s_barrier
	s_add_i32 s40, 0, 0x1c000
	s_add_u32 s18, s14, 0x4000
	s_addc_u32 s19, s15, 0
	s_add_i32 s39, s39, s23
	v_add_u32_e32 v152, s40, v170
	v_lshl_add_u64 v[210:211], s[18:19], 0, v[156:157]
	s_mov_b32 m0, s39
	ds_read_b128 v[194:197], v152
	ds_read_b128 v[198:201], v152 offset:1024
	ds_read_b128 v[202:205], v152 offset:2048
	ds_read_b128 v[206:209], v152 offset:3072
	global_load_lds_dwordx4 v[210:211], off
	s_add_i32 m0, s39, 0x2000
	v_lshl_add_u64 v[210:211], s[18:19], 0, v[158:159]
	global_load_lds_dwordx4 v[210:211], off
	s_barrier
	s_waitcnt lgkmcnt(0)
	s_setprio 1
	v_mfma_f32_16x16x32_bf16 v[116:119], v[194:197], v[144:147], v[116:119]
	v_mfma_f32_16x16x32_bf16 v[112:115], v[202:205], v[144:147], v[112:115]
	s_mov_b32 m0, s29
	v_lshl_add_u64 v[210:211], s[16:17], 0, v[156:157]
	v_mfma_f32_16x16x32_bf16 v[100:103], v[194:197], v[166:169], v[100:103]
	v_mfma_f32_16x16x32_bf16 v[96:99], v[202:205], v[166:169], v[96:99]
	v_mfma_f32_16x16x32_bf16 v[84:87], v[194:197], v[178:181], v[84:87]
	v_mfma_f32_16x16x32_bf16 v[80:83], v[202:205], v[178:181], v[80:83]
	v_mfma_f32_16x16x32_bf16 v[68:71], v[194:197], v[186:189], v[68:71]
	v_mfma_f32_16x16x32_bf16 v[64:67], v[202:205], v[186:189], v[64:67]
	v_mfma_f32_16x16x32_bf16 v[116:119], v[198:201], v[148:151], v[116:119]
	v_mfma_f32_16x16x32_bf16 v[112:115], v[206:209], v[148:151], v[112:115]
	v_mfma_f32_16x16x32_bf16 v[100:103], v[198:201], v[174:177], v[100:103]
	v_mfma_f32_16x16x32_bf16 v[96:99], v[206:209], v[174:177], v[96:99]
	v_mfma_f32_16x16x32_bf16 v[84:87], v[198:201], v[182:185], v[84:87]
	v_mfma_f32_16x16x32_bf16 v[80:83], v[206:209], v[182:185], v[80:83]
	v_mfma_f32_16x16x32_bf16 v[68:71], v[198:201], v[190:193], v[68:71]
	s_setprio 0
	v_mfma_f32_16x16x32_bf16 v[64:67], v[206:209], v[190:193], v[64:67]
	s_barrier
	ds_read_b128 v[144:147], v172 offset:49152
	ds_read_b128 v[148:151], v172 offset:50176
	ds_read_b128 v[166:169], v172 offset:51200
	ds_read_b128 v[174:177], v172 offset:52224
	ds_read_b128 v[178:181], v172 offset:53248
	ds_read_b128 v[182:185], v172 offset:54272
	ds_read_b128 v[186:189], v172 offset:55296
	ds_read_b128 v[190:193], v172 offset:56320
	global_load_lds_dwordx4 v[210:211], off
	s_mov_b32 m0, s30
	v_lshl_add_u64 v[210:211], s[16:17], 0, v[158:159]
	global_load_lds_dwordx4 v[210:211], off
	s_barrier
; #define PG8_STAGE(bufoff, gbase, voff) do { _Pragma("unroll") for (int _i = 0; _i < 2; ++_i) \
;         __builtin_amdgcn_global_load_lds((const unsigned*)((const char*)(gbase) + (voff)[_i]), (LAS unsigned*)(lds + (bufoff) + ldsw + _i * 8192), 16, 0, 0); } while (0)
; #define PG8_MMA(ai, bj, At, Bt) do { __builtin_amdgcn_s_setprio(1); _Pragma("unroll") for (int m = 0; m < 4; ++m) _Pragma("unroll") for (int n = 0; n < 2; ++n) _Pragma("unroll") for (int k = 0; k < 2; ++k) \
;         acc[ai][bj][m][n] = __builtin_amdgcn_mfma_f32_16x16x32_bf16(Bt[n][k], At[m][k], acc[ai][bj][m][n], 0, 0, 0); __builtin_amdgcn_s_setprio(0); } while (0)
; #define PG8_WAIT_V(n) asm volatile("s_waitcnt vmcnt(" #n ")" ::: "memory")
; #define PG8_WAIT_L(n) asm volatile("s_waitcnt lgkmcnt(" #n ")" ::: "memory")
; #define PG8_BAR __builtin_amdgcn_s_barrier()
; #define PG8_SCHED __builtin_amdgcn_sched_barrier(0)
; template <class Epi>
; __device__ __forceinline__ void gemm_phase(LAS unsigned char* lds, const Gemm g, const StaticOrder& S, const Epi& E) {
;     ...
;             PG8_BAR; PG8_WAIT_L(0); PG8_MMA(1, 0, At, B0); PG8_BAR; PG8_SCHED;
;             PG8_STAGE(PG8_SB(1, 1), b3 + hstepB, voffB);
;             PG8_WAIT_V(6); PG8_BAR; PG8_MMA(1, 1, At, B1); PG8_BAR;
;     __device__ __forceinline__ void operator()(const f32x4 (&acc)[2][2][4][2], const Unit& u, int wr, int wc, int fr, int fq) const {
;         const int row0 = u.pm * BM + wr * 64 + fr, j0 = wc * 16 + 4 * fq, colb = u.pn * BM + j0;
;         if (u.pn < 8) {
	s_waitcnt lgkmcnt(0)
	s_setprio 1
	v_mfma_f32_16x16x32_bf16 v[60:63], v[128:131], v[144:147], v[60:63]
	v_mfma_f32_16x16x32_bf16 v[56:59], v[136:139], v[144:147], v[56:59]
	v_mfma_f32_16x16x32_bf16 v[44:47], v[128:131], v[166:169], v[44:47]
	v_mfma_f32_16x16x32_bf16 v[40:43], v[136:139], v[166:169], v[40:43]
	v_mfma_f32_16x16x32_bf16 v[28:31], v[128:131], v[178:181], v[28:31]
	v_mfma_f32_16x16x32_bf16 v[24:27], v[136:139], v[178:181], v[24:27]
	v_mfma_f32_16x16x32_bf16 v[12:15], v[128:131], v[186:189], v[12:15]
	v_mfma_f32_16x16x32_bf16 v[8:11], v[136:139], v[186:189], v[8:11]
	v_mfma_f32_16x16x32_bf16 v[60:63], v[132:135], v[148:151], v[60:63]
	v_mfma_f32_16x16x32_bf16 v[56:59], v[140:143], v[148:151], v[56:59]
	v_mfma_f32_16x16x32_bf16 v[44:47], v[132:135], v[174:177], v[44:47]
	v_mfma_f32_16x16x32_bf16 v[40:43], v[140:143], v[174:177], v[40:43]
	v_mfma_f32_16x16x32_bf16 v[28:31], v[132:135], v[182:185], v[28:31]
	v_mfma_f32_16x16x32_bf16 v[24:27], v[140:143], v[182:185], v[24:27]
	v_mfma_f32_16x16x32_bf16 v[12:15], v[132:135], v[190:193], v[12:15]
	s_setprio 0
	v_mfma_f32_16x16x32_bf16 v[8:11], v[140:143], v[190:193], v[8:11]
	s_barrier
	s_add_u32 s14, s14, 0x84000
	s_addc_u32 s15, s15, 0
	s_add_i32 s16, s40, s23
	s_mov_b32 m0, s16
	v_lshl_add_u64 v[128:129], s[14:15], 0, v[156:157]
	global_load_lds_dwordx4 v[128:129], off
	s_add_i32 m0, s16, 0x2000
	v_lshl_add_u64 v[128:129], s[14:15], 0, v[158:159]
	global_load_lds_dwordx4 v[128:129], off
	s_waitcnt vmcnt(6)
	s_barrier
	s_setprio 1
	v_mfma_f32_16x16x32_bf16 v[52:55], v[194:197], v[144:147], v[52:55]
	v_mfma_f32_16x16x32_bf16 v[48:51], v[202:205], v[144:147], v[48:51]
	s_add_i32 s38, s38, 2
	s_add_u32 s12, s12, 0x8000
	s_addc_u32 s13, s13, 0
	s_add_u32 s36, s36, 0x8000
	s_addc_u32 s37, s37, 0
	v_mfma_f32_16x16x32_bf16 v[36:39], v[194:197], v[166:169], v[36:39]
	v_mfma_f32_16x16x32_bf16 v[32:35], v[202:205], v[166:169], v[32:35]
	v_mfma_f32_16x16x32_bf16 v[20:23], v[194:197], v[178:181], v[20:23]
	v_mfma_f32_16x16x32_bf16 v[16:19], v[202:205], v[178:181], v[16:19]
	v_mfma_f32_16x16x32_bf16 v[4:7], v[194:197], v[186:189], v[4:7]
	v_mfma_f32_16x16x32_bf16 v[0:3], v[202:205], v[186:189], v[0:3]
	v_mfma_f32_16x16x32_bf16 v[52:55], v[198:201], v[148:151], v[52:55]
	v_mfma_f32_16x16x32_bf16 v[48:51], v[206:209], v[148:151], v[48:51]
	v_mfma_f32_16x16x32_bf16 v[36:39], v[198:201], v[174:177], v[36:39]
	v_mfma_f32_16x16x32_bf16 v[32:35], v[206:209], v[174:177], v[32:35]
	v_mfma_f32_16x16x32_bf16 v[20:23], v[198:201], v[182:185], v[20:23]
	v_mfma_f32_16x16x32_bf16 v[16:19], v[206:209], v[182:185], v[16:19]
	v_mfma_f32_16x16x32_bf16 v[4:7], v[198:201], v[190:193], v[4:7]
	s_cmp_gt_u32 s38, 29
	s_setprio 0
	v_mfma_f32_16x16x32_bf16 v[0:3], v[206:209], v[190:193], v[0:3]
	s_barrier
	s_cbranch_scc0 .LBB0_247
	v_lshl_add_u32 v177, s10, 8, v165
	v_lshl_or_b32 v152, s34, 8, v171
	s_mov_b64 s[10:11], -1
	s_cmp_lt_i32 s34, 8
	v_or_b32_e32 v180, 16, v177
	v_or_b32_e32 v179, 32, v177
	v_or_b32_e32 v178, 48, v177
	v_add_u32_e32 v176, 0x80, v177
	v_add_u32_e32 v175, 0x90, v177
	v_add_u32_e32 v174, 0xa0, v177
	v_add_u32_e32 v173, 0xb0, v177
	s_cbranch_scc1 .LBB0_250
; __device__ __forceinline__ unsigned cvt_pk_bf16(float lo, float hi) { unsigned r; asm volatile("v_cvt_pk_bf16_f32 %0, %1, %2" : "=v"(r) : "v"(lo), "v"(hi)); return r; }
;     __device__ __forceinline__ void operator()(const f32x4 (&acc)[2][2][4][2], const Unit& u, int wr, int wc, int fr, int fq) const {
;     ...
; #pragma unroll
;             for (int ai = 0; ai < 2; ++ai)
; #pragma unroll
;                 for (int m = 0; m < 4; ++m) {
;                     const int row = row0 + ai * HALF + m * 16;
;                     bf16_t* rowp = O + (size_t)row * DIN + colb;
; #pragma unroll
;                     for (int bj = 0; bj < 2; ++bj) {
;                         const f32x4 o1 = acc[ai][bj][m][0], o2 = acc[ai][bj][m][1];
;                         u32x2 w1, w2; w1.x = cvt_pk_bf16(o1[0], o1[1]); w1.y = cvt_pk_bf16(o1[2], o1[3]); w2.x = cvt_pk_bf16(o2[0], o2[1]); w2.y = cvt_pk_bf16(o2[2], o2[3]);
;                         *(u32x2*)(rowp + bj * HALF) = w1; *(u32x2*)(rowp + bj * HALF + 64) = w2;
;                     }
;                 }
	v_readlane_b32 s10, v252, 57
	v_readlane_b32 s11, v252, 58
	s_movk_i32 s3, 0x3000
	v_lshlrev_b64 v[130:131], 1, v[152:153]
	v_mov_b64_e32 v[128:129], s[10:11]
	v_mad_i64_i32 v[132:133], s[10:11], v177, s3, v[128:129]
	v_lshl_add_u64 v[132:133], v[132:133], 0, v[130:131]
	v_cvt_pk_bf16_f32 v134, v124, v125
	v_cvt_pk_bf16_f32 v135, v126, v127
	v_cvt_pk_bf16_f32 v136, v120, v121
	v_cvt_pk_bf16_f32 v137, v122, v123
	global_store_dwordx2 v[132:133], v[134:135], off
	global_store_dwordx2 v[132:133], v[136:137], off offset:128
	v_cvt_pk_bf16_f32 v134, v116, v117
	v_cvt_pk_bf16_f32 v135, v118, v119
	v_cvt_pk_bf16_f32 v136, v112, v113
	v_cvt_pk_bf16_f32 v137, v114, v115
	global_store_dwordx2 v[132:133], v[134:135], off offset:256
	global_store_dwordx2 v[132:133], v[136:137], off offset:384
	v_mad_i64_i32 v[132:133], s[10:11], v180, s3, v[128:129]
	v_lshl_add_u64 v[132:133], v[132:133], 0, v[130:131]
	v_cvt_pk_bf16_f32 v134, v108, v109
	v_cvt_pk_bf16_f32 v135, v110, v111
	v_cvt_pk_bf16_f32 v136, v104, v105
	v_cvt_pk_bf16_f32 v137, v106, v107
	global_store_dwordx2 v[132:133], v[134:135], off
	global_store_dwordx2 v[132:133], v[136:137], off offset:128
	v_cvt_pk_bf16_f32 v134, v100, v101
	v_cvt_pk_bf16_f32 v135, v102, v103
	v_cvt_pk_bf16_f32 v136, v96, v97
	v_cvt_pk_bf16_f32 v137, v98, v99
	global_store_dwordx2 v[132:133], v[134:135], off offset:256
	global_store_dwordx2 v[132:133], v[136:137], off offset:384
	v_mad_i64_i32 v[132:133], s[10:11], v179, s3, v[128:129]
	v_lshl_add_u64 v[132:133], v[132:133], 0, v[130:131]
	v_cvt_pk_bf16_f32 v134, v92, v93
	v_cvt_pk_bf16_f32 v135, v94, v95
	v_cvt_pk_bf16_f32 v136, v88, v89
	v_cvt_pk_bf16_f32 v137, v90, v91
	global_store_dwordx2 v[132:133], v[134:135], off
	global_store_dwordx2 v[132:133], v[136:137], off offset:128
	v_cvt_pk_bf16_f32 v134, v84, v85
	v_cvt_pk_bf16_f32 v135, v86, v87
	v_cvt_pk_bf16_f32 v136, v80, v81
	v_cvt_pk_bf16_f32 v137, v82, v83
	global_store_dwordx2 v[132:133], v[134:135], off offset:256
	global_store_dwordx2 v[132:133], v[136:137], off offset:384
	v_mad_i64_i32 v[132:133], s[10:11], v178, s3, v[128:129]
	v_lshl_add_u64 v[132:133], v[132:133], 0, v[130:131]
	v_cvt_pk_bf16_f32 v134, v76, v77
	v_cvt_pk_bf16_f32 v135, v78, v79
	v_cvt_pk_bf16_f32 v136, v72, v73
	v_cvt_pk_bf16_f32 v137, v74, v75
	global_store_dwordx2 v[132:133], v[134:135], off
	global_store_dwordx2 v[132:133], v[136:137], off offset:128
	v_cvt_pk_bf16_f32 v134, v68, v69
	v_cvt_pk_bf16_f32 v135, v70, v71
	v_cvt_pk_bf16_f32 v136, v64, v65
	v_cvt_pk_bf16_f32 v137, v66, v67
	global_store_dwordx2 v[132:133], v[134:135], off offset:256
	global_store_dwordx2 v[132:133], v[136:137], off offset:384
	v_mad_i64_i32 v[132:133], s[10:11], v176, s3, v[128:129]
	v_lshl_add_u64 v[132:133], v[132:133], 0, v[130:131]
	v_cvt_pk_bf16_f32 v134, v60, v61
	v_cvt_pk_bf16_f32 v135, v62, v63
	v_cvt_pk_bf16_f32 v136, v56, v57
	v_cvt_pk_bf16_f32 v137, v58, v59
	global_store_dwordx2 v[132:133], v[134:135], off
	global_store_dwordx2 v[132:133], v[136:137], off offset:128
	v_cvt_pk_bf16_f32 v134, v52, v53
	v_cvt_pk_bf16_f32 v135, v54, v55
	v_cvt_pk_bf16_f32 v136, v48, v49
	v_cvt_pk_bf16_f32 v137, v50, v51
	global_store_dwordx2 v[132:133], v[134:135], off offset:256
	global_store_dwordx2 v[132:133], v[136:137], off offset:384
	v_mad_i64_i32 v[132:133], s[10:11], v175, s3, v[128:129]
	v_lshl_add_u64 v[132:133], v[132:133], 0, v[130:131]
	v_cvt_pk_bf16_f32 v134, v44, v45
	v_cvt_pk_bf16_f32 v135, v46, v47
	v_cvt_pk_bf16_f32 v136, v40, v41
	v_cvt_pk_bf16_f32 v137, v42, v43
	global_store_dwordx2 v[132:133], v[134:135], off
	global_store_dwordx2 v[132:133], v[136:137], off offset:128
	v_cvt_pk_bf16_f32 v134, v36, v37
	v_cvt_pk_bf16_f32 v135, v38, v39
	v_cvt_pk_bf16_f32 v136, v32, v33
	v_cvt_pk_bf16_f32 v137, v34, v35
	global_store_dwordx2 v[132:133], v[134:135], off offset:256
	global_store_dwordx2 v[132:133], v[136:137], off offset:384
	v_mad_i64_i32 v[132:133], s[10:11], v174, s3, v[128:129]
	v_lshl_add_u64 v[132:133], v[132:133], 0, v[130:131]
	v_cvt_pk_bf16_f32 v134, v28, v29
	v_cvt_pk_bf16_f32 v135, v30, v31
	v_cvt_pk_bf16_f32 v136, v24, v25
	v_cvt_pk_bf16_f32 v137, v26, v27
	global_store_dwordx2 v[132:133], v[134:135], off
	global_store_dwordx2 v[132:133], v[136:137], off offset:128
	v_cvt_pk_bf16_f32 v134, v20, v21
	v_cvt_pk_bf16_f32 v135, v22, v23
	v_mad_i64_i32 v[128:129], s[10:11], v173, s3, v[128:129]
	v_cvt_pk_bf16_f32 v136, v16, v17
	v_cvt_pk_bf16_f32 v137, v18, v19
	global_store_dwordx2 v[132:133], v[134:135], off offset:256
	global_store_dwordx2 v[132:133], v[136:137], off offset:384
	v_lshl_add_u64 v[128:129], v[128:129], 0, v[130:131]
	v_cvt_pk_bf16_f32 v130, v12, v13
	v_cvt_pk_bf16_f32 v131, v14, v15
	v_cvt_pk_bf16_f32 v132, v8, v9
	v_cvt_pk_bf16_f32 v133, v10, v11
	s_mov_b64 s[10:11], 0
	global_store_dwordx2 v[128:129], v[130:131], off
	global_store_dwordx2 v[128:129], v[132:133], off offset:128
	v_cvt_pk_bf16_f32 v130, v4, v5
	v_cvt_pk_bf16_f32 v131, v6, v7
	v_cvt_pk_bf16_f32 v132, v0, v1
	v_cvt_pk_bf16_f32 v133, v2, v3
